# conv-loop store-drain wait removed; EpiT2 and EpiNorm pass-1 epilogue loads software-pipelined; P0 row loop: b_i/b_f hoisted to SGPRs (16 load round-trips per trip removed), vmcnt re-derived
# speedup vs baseline: 1.0191x; 1.0191x over previous
.LBB0_23:
	s_or_b64 exec, exec, s[0:1]
	s_movk_i32 s24, 0x4200
	v_cmp_gt_i32_e32 vcc, s24, v42
	v_mbcnt_lo_u32_b32 v185, -1, 0
	s_waitcnt lgkmcnt(0)
	s_barrier
	s_and_saveexec_b64 s[0:1], vcc
	s_cbranch_execz .LBB0_31
	v_readlane_b32 s20, v254, 5
	v_readlane_b32 s21, v254, 6
	v_readlane_b32 s22, v254, 7
	v_readlane_b32 s23, v254, 8
	s_nop 4
	s_load_dwordx4 s[76:79], s[20:21], 0x0
	s_load_dwordx4 s[80:83], s[22:23], 0x0
	v_lshlrev_b32_e32 v1, 4, v148
	global_load_dwordx4 v[2:5], v1, s[64:65]
	global_load_dwordx4 v[6:9], v1, s[64:65] offset:1024
	global_load_dwordx4 v[10:13], v1, s[64:65] offset:2048
	global_load_dwordx4 v[14:17], v1, s[64:65] offset:3072
	v_mbcnt_hi_u32_b32 v18, -1, v185
	v_and_b32_e32 v19, 64, v18
	v_add_u32_e32 v19, 64, v19
	v_xor_b32_e32 v20, 1, v18
	v_cmp_lt_i32_e32 vcc, v20, v19
	s_lshl_b32 s6, s90, 4
	v_ashrrev_i32_e32 v43, 31, v42
	v_cndmask_b32_e32 v20, v18, v20, vcc
	v_lshlrev_b32_e32 v66, 2, v20
	v_xor_b32_e32 v20, 2, v18
	v_cmp_lt_i32_e32 vcc, v20, v19
	s_ashr_i32 s7, s6, 31
	v_lshlrev_b64 v[50:51], 11, v[42:43]
	v_cndmask_b32_e32 v20, v18, v20, vcc
	v_lshlrev_b32_e32 v67, 2, v20
	v_xor_b32_e32 v20, 4, v18
	v_cmp_lt_i32_e32 vcc, v20, v19
	v_mov_b32_e32 v45, 0
	v_add_u32_e32 v1, s73, v1
	v_cndmask_b32_e32 v20, v18, v20, vcc
	v_lshlrev_b32_e32 v68, 2, v20
	v_xor_b32_e32 v20, 8, v18
	v_cmp_lt_i32_e32 vcc, v20, v19
	v_cmp_eq_u32_e64 s[2:3], 0, v148
	s_lshl_b64 s[8:9], s[6:7], 5
	v_cndmask_b32_e32 v20, v18, v20, vcc
	v_lshlrev_b32_e32 v69, 2, v20
	v_xor_b32_e32 v20, 16, v18
	v_cmp_lt_i32_e32 vcc, v20, v19
	s_lshl_b64 s[10:11], s[6:7], 11
	v_lshlrev_b64 v[52:53], 5, v[42:43]
	v_cndmask_b32_e32 v20, v18, v20, vcc
	v_lshlrev_b32_e32 v70, 2, v20
	v_xor_b32_e32 v20, 32, v18
	v_cmp_lt_i32_e32 vcc, v20, v19
	s_mov_b64 s[12:13], 0
	s_movk_i32 s25, 0x4000
	v_cndmask_b32_e32 v18, v18, v20, vcc
	v_lshlrev_b32_e32 v71, 2, v18
	v_add_u32_e32 v18, s33, v42
	v_ashrrev_i32_e32 v19, 31, v18
	v_lshlrev_b64 v[46:47], 5, v[18:19]
	v_lshlrev_b64 v[48:49], 11, v[18:19]
	v_lshlrev_b32_e32 v18, 3, v148
	v_or_b32_e32 v48, v48, v18
	v_or_b32_e32 v50, v50, v18
	v_mov_b32_e32 v72, s55
	v_mov_b32_e32 v73, s53
	v_lshlrev_b32_e32 v44, 4, v148
	v_mov_b32_e32 v74, 0x358637bd
	s_mov_b32 s28, 0x800000
	s_mov_b32 s29, 0x276e000
	s_mov_b32 s30, 0xbfb8aa3b
	s_mov_b32 s31, 0xb2a5705f
	s_mov_b32 s34, 0x42ce8ed0
	s_mov_b32 s35, 0xc2b17218
	s_mov_b32 s64, 0x7f800000
	s_mov_b32 s65, 0x3f2aaaab
	v_mov_b32_e32 v75, 0x3ecc95a3
	s_mov_b32 s66, 0x3f317218
	s_mov_b32 s67, 0x33800000
	s_movk_i32 s84, 0x41ff
	v_mov_b32_e32 v76, 0x7f800000
	s_branch .LBB0_26

.LBB0_26:
	v_add_u32_e32 v18, 0xffffc000, v42
	v_cmp_gt_i32_e32 vcc, s25, v42
	v_mov_b32_e32 v29, s54
	v_mov_b32_e32 v32, s52
	v_cndmask_b32_e32 v19, 0, v43, vcc
	v_cndmask_b32_e32 v18, v18, v42, vcc
	s_waitcnt lgkmcnt(0)
	v_cndmask_b32_e32 v21, v72, v73, vcc
	v_cndmask_b32_e32 v20, v29, v32, vcc
	v_lshlrev_b64 v[18:19], 12, v[18:19]
	v_lshl_add_u64 v[18:19], v[20:21], 0, v[18:19]
	v_lshl_add_u64 v[18:19], v[18:19], 0, v[44:45]
	global_load_dwordx4 v[56:59], v[18:19], off
	global_load_dwordx4 v[60:63], v[18:19], off offset:1024
	global_load_dwordx4 v[34:37], v[18:19], off offset:3072
	global_load_dwordx4 v[38:41], v[18:19], off offset:2048
	s_waitcnt vmcnt(3)
	v_pk_mul_f32 v[18:19], v[58:59], v[58:59]
	v_pk_mul_f32 v[20:21], v[56:57], v[56:57]
	s_waitcnt vmcnt(2)
	v_pk_mul_f32 v[22:23], v[62:63], v[62:63]
	v_pk_mul_f32 v[24:25], v[60:61], v[60:61]
	v_pk_mov_b32 v[30:31], v[20:21], v[18:19] op_sel:[1,0]
	v_mov_b32_e32 v21, v19
	v_pk_mov_b32 v[18:19], v[24:25], v[22:23] op_sel:[1,0]
	v_mov_b32_e32 v25, v23
	s_waitcnt vmcnt(0)
	v_mul_f32_e32 v26, v39, v39
	v_mul_f32_e32 v28, v41, v41
	v_pk_add_f32 v[20:21], v[30:31], v[20:21]
	v_pk_add_f32 v[18:19], v[18:19], v[24:25]
	v_mul_f32_e32 v33, v34, v34
	v_mul_f32_e32 v54, v35, v35
	v_mul_f32_e32 v55, v36, v36
	v_mul_f32_e32 v64, v37, v37
	v_pk_fma_f32 v[22:23], v[38:39], v[38:39], v[26:27] op_sel_hi:[1,1,0]
	v_pk_fma_f32 v[26:27], v[40:41], v[40:41], v[28:29] op_sel_hi:[1,1,0]
	v_pk_add_f32 v[20:21], v[20:21], v[20:21] op_sel:[0,1] op_sel_hi:[1,0]
	v_pk_add_f32 v[18:19], v[18:19], v[18:19] op_sel:[0,1] op_sel_hi:[1,0]
	v_mov_b32_e32 v23, v55
	v_mov_b32_e32 v27, v64
	v_mov_b32_e32 v21, v33
	v_mov_b32_e32 v19, v54
	v_pk_add_f32 v[22:23], v[22:23], v[26:27]
	v_pk_add_f32 v[18:19], v[20:21], v[18:19]
	v_add_u32_e32 v20, s33, v42
	v_pk_add_f32 v[18:19], v[18:19], v[22:23]
	v_cmp_gt_i32_e64 s[4:5], s24, v20
	v_add_f32_e32 v18, v18, v19
	ds_bpermute_b32 v19, v66, v18
	v_cndmask_b32_e64 v20, v42, v20, s[4:5]
	v_add_u32_e32 v25, 0xffffc000, v20
	v_mov_b32_e32 v21, s55
	v_mov_b32_e32 v24, s53
	s_waitcnt lgkmcnt(0)
	v_add_f32_e32 v18, v18, v19
	ds_bpermute_b32 v19, v67, v18
	s_waitcnt lgkmcnt(0)
	v_add_f32_e32 v22, v18, v19
	ds_bpermute_b32 v23, v68, v22
	v_lshl_add_u64 v[18:19], s[74:75], 0, v[50:51]
	v_add_co_u32_e32 v54, vcc, s29, v18
	v_ashrrev_i32_e32 v18, 31, v20
	s_waitcnt lgkmcnt(0)
	v_add_f32_e32 v22, v22, v23
	ds_bpermute_b32 v23, v69, v22
	v_addc_co_u32_e32 v55, vcc, 0, v19, vcc
	v_cmp_gt_i32_e32 vcc, s25, v20
	s_waitcnt lgkmcnt(0)
	v_add_f32_e32 v22, v22, v23
	ds_bpermute_b32 v23, v70, v22
	v_cndmask_b32_e32 v19, 0, v18, vcc
	v_cndmask_b32_e32 v18, v25, v20, vcc
	v_cndmask_b32_e32 v21, v21, v24, vcc
	v_cndmask_b32_e32 v20, v29, v32, vcc
	s_waitcnt lgkmcnt(0)
	v_add_f32_e32 v22, v22, v23
	ds_bpermute_b32 v23, v71, v22
	v_lshlrev_b64 v[18:19], 12, v[18:19]
	v_lshl_add_u64 v[18:19], v[20:21], 0, v[18:19]
	v_lshl_add_u64 v[18:19], v[18:19], 0, v[44:45]
	s_waitcnt lgkmcnt(0)
	v_add_f32_e32 v20, v22, v23
	v_fmamk_f32 v20, v20, 0x3a800000, v74
	v_mul_f32_e32 v21, 0x4b800000, v20
	v_cmp_gt_f32_e32 vcc, s28, v20
	s_nop 1
	v_cndmask_b32_e32 v20, v20, v21, vcc
	v_rsq_f32_e32 v64, v20
	global_load_dwordx4 v[30:33], v[18:19], off
	global_load_dwordx4 v[26:29], v[18:19], off offset:1024
	global_load_dwordx4 v[22:25], v[18:19], off offset:2048
	s_nop 0
	global_load_dwordx4 v[18:21], v[18:19], off offset:3072
	v_mul_f32_e32 v65, 0x45800000, v64
	v_cndmask_b32_e32 v64, v64, v65, vcc
	v_pk_mul_f32 v[56:57], v[56:57], v[64:65] op_sel_hi:[1,0]
	v_pk_mul_f32 v[58:59], v[58:59], v[64:65] op_sel_hi:[1,0]
	v_pk_mul_f32 v[38:39], v[38:39], v[64:65] op_sel_hi:[1,0]
	v_pk_mul_f32 v[34:35], v[34:35], v[64:65] op_sel_hi:[1,0]
	v_pk_mul_f32 v[60:61], v[60:61], v[64:65] op_sel_hi:[1,0]
	v_pk_mul_f32 v[78:79], v[62:63], v[64:65] op_sel_hi:[1,0]
	v_pk_mul_f32 v[40:41], v[40:41], v[64:65] op_sel_hi:[1,0]
	v_pk_mul_f32 v[36:37], v[36:37], v[64:65] op_sel_hi:[1,0]
	v_pk_mul_f32 v[62:63], v[4:5], v[58:59]
	v_pk_mul_f32 v[64:65], v[2:3], v[56:57]
	v_pk_mul_f32 v[56:57], v[10:11], v[38:39]
	v_pk_mul_f32 v[38:39], v[14:15], v[34:35]
	v_cvt_pk_bf16_f32 v34, v64, v65
	v_cvt_pk_bf16_f32 v35, v62, v63
	v_pk_mul_f32 v[58:59], v[8:9], v[78:79]
	v_pk_mul_f32 v[60:61], v[6:7], v[60:61]
	global_store_dwordx2 v[54:55], v[34:35], off
	v_cvt_pk_bf16_f32 v34, v60, v61
	v_cvt_pk_bf16_f32 v35, v58, v59
	v_pk_mul_f32 v[40:41], v[12:13], v[40:41]
	global_store_dwordx2 v[54:55], v[34:35], off offset:512
	v_cvt_pk_bf16_f32 v34, v56, v57
	v_cvt_pk_bf16_f32 v35, v40, v41
	v_pk_mul_f32 v[36:37], v[16:17], v[36:37]
	global_store_dwordx2 v[54:55], v[34:35], off offset:1024
	v_cvt_pk_bf16_f32 v34, v38, v39
	v_cvt_pk_bf16_f32 v35, v36, v37
	ds_read_b128 v[78:81], v1
	ds_read_b128 v[82:85], v1 offset:1024
	ds_read_b128 v[86:89], v1 offset:2048
	ds_read_b128 v[90:93], v1 offset:3072
	ds_read_b128 v[94:97], v1 offset:4096
	ds_read_b128 v[98:101], v1 offset:5120
	ds_read_b128 v[102:105], v1 offset:6144
	ds_read_b128 v[106:109], v1 offset:7168
	s_waitcnt lgkmcnt(7)
	v_mul_f32_e32 v77, v65, v79
	v_mul_f32_e32 v79, v63, v81
	s_waitcnt lgkmcnt(6)
	v_mul_f32_e32 v81, v61, v83
	v_mul_f32_e32 v83, v59, v85
	v_fmac_f32_e32 v77, v64, v78
	v_fmac_f32_e32 v79, v62, v80
	s_waitcnt lgkmcnt(5)
	v_mul_f32_e32 v85, v57, v87
	v_mul_f32_e32 v87, v41, v89
	v_fmac_f32_e32 v81, v60, v82
	v_fmac_f32_e32 v83, v58, v84
	v_add_f32_e32 v77, v77, v79
	s_waitcnt lgkmcnt(4)
	v_mul_f32_e32 v89, v39, v91
	v_mul_f32_e32 v91, v37, v93
	v_fmac_f32_e32 v85, v56, v86
	v_fmac_f32_e32 v87, v40, v88
	v_add_f32_e32 v78, v81, v83
	v_add_f32_e32 v77, 0, v77
	v_fmac_f32_e32 v89, v38, v90
	v_fmac_f32_e32 v91, v36, v92
	v_add_f32_e32 v79, v85, v87
	v_add_f32_e32 v77, v77, v78
	s_waitcnt lgkmcnt(3)
	v_mul_f32_e32 v93, v65, v95
	v_mul_f32_e32 v95, v63, v97
	v_add_f32_e32 v80, v89, v91
	v_add_f32_e32 v77, v77, v79
	s_waitcnt lgkmcnt(2)
	v_mul_f32_e32 v97, v61, v99
	v_mul_f32_e32 v99, v59, v101
	v_fmac_f32_e32 v93, v64, v94
	v_fmac_f32_e32 v95, v62, v96
	v_add_f32_e32 v77, v77, v80
	v_fmac_f32_e32 v97, v60, v98
	v_fmac_f32_e32 v99, v58, v100
	ds_bpermute_b32 v78, v66, v77
	v_add_f32_e32 v79, v93, v95
	v_add_f32_e32 v80, v97, v99
	v_add_f32_e32 v79, 0, v79
	s_waitcnt lgkmcnt(2)
	v_mul_f32_e32 v101, v57, v103
	v_add_f32_e32 v79, v79, v80
	v_mul_f32_e32 v80, v41, v105
	v_fmac_f32_e32 v101, v56, v102
	v_fmac_f32_e32 v80, v40, v104
	v_add_f32_e32 v80, v101, v80
	s_waitcnt lgkmcnt(0)
	v_add_f32_e32 v77, v77, v78
	v_add_f32_e32 v79, v79, v80
	v_mul_f32_e32 v80, v39, v107
	v_mul_f32_e32 v81, v37, v109
	ds_bpermute_b32 v78, v67, v77
	v_fmac_f32_e32 v80, v38, v106
	v_fmac_f32_e32 v81, v36, v108
	v_add_f32_e32 v80, v80, v81
	v_add_f32_e32 v79, v79, v80
	ds_bpermute_b32 v80, v66, v79
	s_waitcnt lgkmcnt(1)
	v_add_f32_e32 v77, v77, v78
	ds_bpermute_b32 v78, v68, v77
	global_store_dwordx2 v[54:55], v[34:35], off offset:1536
	s_waitcnt lgkmcnt(1)
	v_add_f32_e32 v82, v79, v80
	ds_bpermute_b32 v83, v67, v82
	s_waitcnt lgkmcnt(1)
	v_add_f32_e32 v77, v77, v78
	ds_read_b128 v[78:81], v1 offset:8192
	ds_bpermute_b32 v86, v69, v77
	s_waitcnt lgkmcnt(2)
	v_add_f32_e32 v87, v82, v83
	ds_read_b128 v[82:85], v1 offset:9216
	s_waitcnt lgkmcnt(2)
	v_mul_f32_e32 v79, v65, v79
	v_fmac_f32_e32 v79, v64, v78
	v_mul_f32_e32 v78, v63, v81
	v_fmac_f32_e32 v78, v62, v80
	v_add_f32_e32 v78, v79, v78
	s_waitcnt lgkmcnt(0)
	v_mul_f32_e32 v83, v61, v83
	v_add_f32_e32 v89, 0, v78
	v_fmac_f32_e32 v83, v60, v82
	v_mul_f32_e32 v82, v59, v85
	ds_read_b128 v[78:81], v1 offset:10240
	v_fmac_f32_e32 v82, v58, v84
	v_add_f32_e32 v82, v83, v82
	v_add_f32_e32 v89, v89, v82
	ds_read_b128 v[82:85], v1 offset:11264
	s_waitcnt lgkmcnt(1)
	v_mul_f32_e32 v79, v57, v79
	v_fmac_f32_e32 v79, v56, v78
	v_mul_f32_e32 v78, v41, v81
	v_fmac_f32_e32 v78, v40, v80
	v_add_f32_e32 v78, v79, v78
	s_waitcnt lgkmcnt(0)
	v_mul_f32_e32 v79, v39, v83
	v_mul_f32_e32 v80, v37, v85
	v_fmac_f32_e32 v79, v38, v82
	v_fmac_f32_e32 v80, v36, v84
	v_add_f32_e32 v78, v89, v78
	v_add_f32_e32 v79, v79, v80
	v_add_f32_e32 v78, v78, v79
	ds_bpermute_b32 v88, v68, v87
	ds_bpermute_b32 v79, v66, v78
	v_add_f32_e32 v77, v77, v86
	ds_bpermute_b32 v80, v70, v77
	s_waitcnt lgkmcnt(2)
	v_add_f32_e32 v84, v87, v88
	s_waitcnt lgkmcnt(1)
	v_add_f32_e32 v79, v78, v79
	ds_bpermute_b32 v85, v69, v84
	ds_bpermute_b32 v86, v67, v79
	s_waitcnt lgkmcnt(2)
	v_add_f32_e32 v77, v77, v80
	ds_read_b128 v[80:83], v1 offset:12288
	ds_bpermute_b32 v78, v71, v77
	s_waitcnt lgkmcnt(3)
	v_add_f32_e32 v88, v84, v85
	s_waitcnt lgkmcnt(2)
	v_add_f32_e32 v79, v79, v86
	ds_read_b128 v[84:87], v1 offset:13312
	s_waitcnt lgkmcnt(2)
	v_mul_f32_e32 v81, v65, v81
	v_fmac_f32_e32 v81, v64, v80
	v_mul_f32_e32 v80, v63, v83
	v_fmac_f32_e32 v80, v62, v82
	v_add_f32_e32 v80, v81, v80
	s_waitcnt lgkmcnt(0)
	v_mul_f32_e32 v85, v61, v85
	v_add_f32_e32 v90, 0, v80
	v_fmac_f32_e32 v85, v60, v84
	v_mul_f32_e32 v84, v59, v87
	ds_read_b128 v[80:83], v1 offset:14336
	v_fmac_f32_e32 v84, v58, v86
	v_add_f32_e32 v84, v85, v84
	v_add_f32_e32 v90, v90, v84
	ds_read_b128 v[84:87], v1 offset:15360
	s_waitcnt lgkmcnt(1)
	v_mul_f32_e32 v81, v57, v81
	v_fmac_f32_e32 v81, v56, v80
	v_mul_f32_e32 v80, v41, v83
	v_fmac_f32_e32 v80, v40, v82
	v_add_f32_e32 v80, v81, v80
	s_waitcnt lgkmcnt(0)
	v_mul_f32_e32 v85, v39, v85
	v_add_f32_e32 v90, v90, v80
	v_fmac_f32_e32 v85, v38, v84
	v_mul_f32_e32 v84, v37, v87
	ds_read_b128 v[80:83], v1 offset:16384
	v_fmac_f32_e32 v84, v36, v86
	v_add_f32_e32 v84, v85, v84
	v_add_f32_e32 v90, v90, v84
	ds_read_b128 v[84:87], v1 offset:17408
	s_waitcnt lgkmcnt(1)
	v_mul_f32_e32 v81, v65, v81
	v_fmac_f32_e32 v81, v64, v80
	v_mul_f32_e32 v80, v63, v83
	v_fmac_f32_e32 v80, v62, v82
	v_add_f32_e32 v80, v81, v80
	s_waitcnt lgkmcnt(0)
	v_mul_f32_e32 v85, v61, v85
	v_add_f32_e32 v92, 0, v80
	v_fmac_f32_e32 v85, v60, v84
	v_mul_f32_e32 v84, v59, v87
	ds_read_b128 v[80:83], v1 offset:18432
	v_fmac_f32_e32 v84, v58, v86
	v_add_f32_e32 v84, v85, v84
	v_add_f32_e32 v92, v92, v84
	ds_read_b128 v[84:87], v1 offset:19456
	s_waitcnt lgkmcnt(1)
	v_mul_f32_e32 v81, v57, v81
	v_fmac_f32_e32 v81, v56, v80
	v_mul_f32_e32 v80, v41, v83
	ds_bpermute_b32 v91, v66, v90
	v_fmac_f32_e32 v80, v40, v82
	v_add_f32_e32 v80, v81, v80
	s_waitcnt lgkmcnt(1)
	v_mul_f32_e32 v81, v39, v85
	v_mul_f32_e32 v82, v37, v87
	v_fmac_f32_e32 v81, v38, v84
	v_fmac_f32_e32 v82, v36, v86
	v_add_f32_e32 v80, v92, v80
	v_add_f32_e32 v81, v81, v82
	v_add_f32_e32 v80, v80, v81
	ds_bpermute_b32 v81, v66, v80
	s_waitcnt lgkmcnt(1)
	v_add_f32_e32 v83, v90, v91
	ds_bpermute_b32 v84, v67, v83
	ds_bpermute_b32 v89, v68, v79
	ds_bpermute_b32 v82, v70, v88
	s_waitcnt lgkmcnt(3)
	v_add_f32_e32 v80, v80, v81
	ds_bpermute_b32 v81, v67, v80
	s_waitcnt lgkmcnt(3)
	v_add_f32_e32 v83, v83, v84
	ds_bpermute_b32 v84, v68, v83
	s_waitcnt lgkmcnt(3)
	v_add_f32_e32 v85, v79, v89
	ds_bpermute_b32 v86, v69, v85
	s_waitcnt lgkmcnt(2)
	v_add_f32_e32 v80, v80, v81
	ds_bpermute_b32 v81, v68, v80
	s_waitcnt lgkmcnt(2)
	v_add_f32_e32 v83, v83, v84
	ds_bpermute_b32 v84, v69, v83
	s_waitcnt lgkmcnt(2)
	v_add_f32_e32 v85, v85, v86
	ds_bpermute_b32 v86, v70, v85
	s_waitcnt lgkmcnt(2)
	v_add_f32_e32 v81, v80, v81
	ds_bpermute_b32 v87, v69, v81
	s_waitcnt lgkmcnt(2)
	v_add_f32_e32 v84, v83, v84
	v_add_f32_e32 v79, v88, v82
	ds_bpermute_b32 v88, v70, v84
	s_waitcnt lgkmcnt(2)
	v_add_f32_e32 v80, v85, v86
	s_waitcnt lgkmcnt(1)
	v_add_f32_e32 v85, v81, v87
	ds_bpermute_b32 v87, v70, v85
	ds_read_b128 v[92:95], v1 offset:21504
	s_waitcnt lgkmcnt(2)
	v_add_f32_e32 v81, v84, v88
	ds_read_b128 v[88:91], v1 offset:20480
	ds_bpermute_b32 v82, v71, v79
	s_waitcnt lgkmcnt(3)
	v_add_f32_e32 v84, v85, v87
	s_waitcnt lgkmcnt(2)
	v_mul_f32_e32 v93, v61, v93
	v_fmac_f32_e32 v93, v60, v92
	s_waitcnt lgkmcnt(1)
	v_mul_f32_e32 v87, v65, v89
	v_fmac_f32_e32 v87, v64, v88
	v_mul_f32_e32 v88, v63, v91
	v_fmac_f32_e32 v88, v62, v90
	v_mul_f32_e32 v92, v59, v95
	v_add_f32_e32 v87, v87, v88
	ds_read_b128 v[88:91], v1 offset:22528
	v_fmac_f32_e32 v92, v58, v94
	v_add_f32_e32 v87, 0, v87
	v_add_f32_e32 v92, v93, v92
	v_add_f32_e32 v87, v87, v92
	ds_read_b128 v[92:95], v1 offset:23552
	s_waitcnt lgkmcnt(1)
	v_mul_f32_e32 v89, v57, v89
	v_fmac_f32_e32 v89, v56, v88
	v_mul_f32_e32 v88, v41, v91
	v_fmac_f32_e32 v88, v40, v90
	s_waitcnt lgkmcnt(0)
	v_mul_f32_e32 v93, v39, v93
	v_add_f32_e32 v88, v89, v88
	v_fmac_f32_e32 v93, v38, v92
	v_mul_f32_e32 v92, v37, v95
	v_add_f32_e32 v87, v87, v88
	v_fmac_f32_e32 v92, v36, v94
	ds_read_b128 v[88:91], v1 offset:24576
	v_add_f32_e32 v92, v93, v92
	v_add_f32_e32 v87, v87, v92
	ds_read_b128 v[92:95], v1 offset:25600
	ds_bpermute_b32 v96, v66, v87
	s_waitcnt lgkmcnt(2)
	v_mul_f32_e32 v89, v65, v89
	v_fmac_f32_e32 v89, v64, v88
	v_mul_f32_e32 v88, v63, v91
	v_fmac_f32_e32 v88, v62, v90
	s_waitcnt lgkmcnt(1)
	v_mul_f32_e32 v93, v61, v93
	v_add_f32_e32 v88, v89, v88
	v_fmac_f32_e32 v93, v60, v92
	v_mul_f32_e32 v92, v59, v95
	v_add_f32_e32 v97, 0, v88
	ds_read_b128 v[88:91], v1 offset:26624
	v_fmac_f32_e32 v92, v58, v94
	v_add_f32_e32 v92, v93, v92
	v_add_f32_e32 v97, v97, v92
	ds_read_b128 v[92:95], v1 offset:27648
	s_waitcnt lgkmcnt(1)
	v_mul_f32_e32 v89, v57, v89
	v_fmac_f32_e32 v89, v56, v88
	v_mul_f32_e32 v88, v41, v91
	v_fmac_f32_e32 v88, v40, v90
	s_waitcnt lgkmcnt(0)
	v_mul_f32_e32 v93, v39, v93
	v_add_f32_e32 v88, v89, v88
	v_fmac_f32_e32 v93, v38, v92
	v_mul_f32_e32 v92, v37, v95
	v_add_f32_e32 v97, v97, v88
	v_fmac_f32_e32 v92, v36, v94
	ds_read_b128 v[88:91], v1 offset:28672
	v_add_f32_e32 v92, v93, v92
	v_add_f32_e32 v97, v97, v92
	ds_read_b128 v[92:95], v1 offset:29696
	ds_bpermute_b32 v98, v66, v97
	s_waitcnt lgkmcnt(2)
	v_mul_f32_e32 v65, v65, v89
	v_mul_f32_e32 v63, v63, v91
	v_fmac_f32_e32 v65, v64, v88
	v_fmac_f32_e32 v63, v62, v90
	v_add_f32_e32 v62, v65, v63
	s_waitcnt lgkmcnt(1)
	v_mul_f32_e32 v65, v61, v93
	v_add_f32_e32 v64, 0, v62
	v_fmac_f32_e32 v65, v60, v92
	ds_read_b128 v[60:63], v1 offset:30720
	ds_read_b128 v[88:91], v1 offset:31744
	v_mul_f32_e32 v59, v59, v95
	v_fmac_f32_e32 v59, v58, v94
	v_add_f32_e32 v58, v65, v59
	s_waitcnt lgkmcnt(1)
	v_mul_f32_e32 v57, v57, v61
	v_mul_f32_e32 v41, v41, v63
	v_fmac_f32_e32 v57, v56, v60
	v_fmac_f32_e32 v41, v40, v62
	s_waitcnt lgkmcnt(0)
	v_mul_f32_e32 v39, v39, v89
	v_mul_f32_e32 v37, v37, v91
	v_add_f32_e32 v58, v64, v58
	v_add_f32_e32 v40, v57, v41
	v_fmac_f32_e32 v39, v38, v88
	v_fmac_f32_e32 v37, v36, v90
	v_add_f32_e32 v40, v58, v40
	v_add_f32_e32 v36, v39, v37
	v_add_f32_e32 v36, v40, v36
	ds_bpermute_b32 v37, v66, v36
	v_add_f32_e32 v38, v87, v96
	v_add_f32_e32 v40, v97, v98
	ds_bpermute_b32 v39, v67, v38
	ds_bpermute_b32 v41, v67, v40
	s_waitcnt lgkmcnt(2)
	v_add_f32_e32 v36, v36, v37
	ds_bpermute_b32 v37, v67, v36
	ds_bpermute_b32 v83, v71, v80
	s_waitcnt lgkmcnt(3)
	v_add_f32_e32 v38, v38, v39
	s_waitcnt lgkmcnt(2)
	v_add_f32_e32 v40, v40, v41
	ds_bpermute_b32 v39, v68, v38
	s_waitcnt lgkmcnt(2)
	v_add_f32_e32 v36, v36, v37
	ds_bpermute_b32 v41, v68, v40
	ds_bpermute_b32 v37, v68, v36
	ds_bpermute_b32 v86, v71, v81
	s_waitcnt lgkmcnt(3)
	v_add_f32_e32 v38, v38, v39
	ds_bpermute_b32 v39, v69, v38
	s_waitcnt lgkmcnt(3)
	v_add_f32_e32 v40, v40, v41
	s_waitcnt lgkmcnt(2)
	v_add_f32_e32 v36, v36, v37
	ds_bpermute_b32 v41, v69, v40
	ds_bpermute_b32 v37, v69, v36
	s_waitcnt lgkmcnt(2)
	v_add_f32_e32 v38, v38, v39
	ds_bpermute_b32 v39, v70, v38
	ds_bpermute_b32 v85, v71, v84
	s_waitcnt lgkmcnt(3)
	v_add_f32_e32 v56, v40, v41
	s_waitcnt lgkmcnt(2)
	v_add_f32_e32 v36, v36, v37
	ds_bpermute_b32 v57, v70, v56
	ds_bpermute_b32 v37, v70, v36
	s_waitcnt lgkmcnt(3)
	v_add_f32_e32 v40, v38, v39
	ds_bpermute_b32 v41, v71, v40
	s_waitcnt lgkmcnt(2)
	v_add_f32_e32 v38, v56, v57
	s_waitcnt lgkmcnt(1)
	v_add_f32_e32 v36, v36, v37
	ds_bpermute_b32 v39, v71, v38
	ds_bpermute_b32 v37, v71, v36
	s_and_saveexec_b64 s[26:27], s[2:3]
	s_waitcnt vmcnt(4)
	s_cbranch_execz .LBB0_28
	v_readlane_b32 s36, v254, 5
	v_readlane_b32 s37, v254, 6
	v_lshl_add_u64 v[34:35], s[74:75], 0, v[52:53]
	v_add_f32_e32 v55, v77, v78
	v_add_co_u32_e32 v34, vcc, 0x26a8000, v34
	v_readlane_b32 s38, v254, 7
	s_nop 0
	v_addc_co_u32_e32 v35, vcc, 0, v35, vcc
	v_readlane_b32 s39, v254, 8
	s_waitcnt lgkmcnt(2)
	v_add_f32_e32 v40, v40, v41
	s_waitcnt lgkmcnt(1)
	v_add_f32_e32 v38, v38, v39
	s_waitcnt lgkmcnt(0)
	v_add_f32_e32 v36, v36, v37
	v_readlane_b32 s40, v254, 9
	v_readlane_b32 s41, v254, 10
	v_readlane_b32 s42, v254, 11
	v_readlane_b32 s43, v254, 12
	v_readlane_b32 s44, v254, 13
	v_readlane_b32 s45, v254, 14
	v_readlane_b32 s46, v254, 15
	v_readlane_b32 s47, v254, 16
	v_readlane_b32 s48, v254, 17
	v_readlane_b32 s49, v254, 18
	v_readlane_b32 s50, v254, 19
	v_readlane_b32 s51, v254, 20
	v_add_f32_e32 v54, s76, v55
	global_store_dword v[34:35], v54, off
	v_add_f32_e32 v55, v79, v82
	v_add_f32_e32 v54, s77, v55
	global_store_dword v[34:35], v54, off offset:4
	v_add_f32_e32 v55, v80, v83
	v_add_f32_e32 v54, s78, v55
	global_store_dword v[34:35], v54, off offset:8
	v_add_f32_e32 v55, v81, v86
	v_add_f32_e32 v54, s79, v55
	global_store_dword v[34:35], v54, off offset:12
	v_add_f32_e32 v55, v84, v85
	v_add_f32_e32 v54, s80, v55
	v_mul_f32_e64 v55, |v54|, s30
	v_fma_f32 v56, |v54|, s30, -v55
	v_rndne_f32_e32 v57, v55
	v_fma_f32 v56, |v54|, s31, v56
	v_sub_f32_e32 v55, v55, v57
	v_add_f32_e32 v55, v55, v56
	v_cvt_i32_f32_e32 v57, v57
	v_exp_f32_e32 v55, v55
	v_cmp_ngt_f32_e64 vcc, |v54|, s34
	v_min_f32_e32 v56, 0, v54
	v_ldexp_f32 v55, v55, v57
	v_cndmask_b32_e32 v55, 0, v55, vcc
	v_cmp_nlt_f32_e64 vcc, |v54|, s35
	s_nop 1
	v_cndmask_b32_e32 v57, v76, v55, vcc
	v_add_f32_e32 v58, 1.0, v57
	v_add_f32_e32 v59, -1.0, v58
	v_frexp_mant_f32_e32 v60, v58
	v_cvt_f64_f32_e32 v[54:55], v58
	v_sub_f32_e32 v61, v59, v58
	v_frexp_exp_i32_f64_e32 v54, v[54:55]
	v_cmp_gt_f32_e32 vcc, s65, v60
	v_sub_f32_e32 v59, v57, v59
	v_add_f32_e32 v55, 1.0, v61
	v_subbrev_co_u32_e32 v54, vcc, 0, v54, vcc
	v_add_f32_e32 v55, v59, v55
	v_sub_u32_e32 v59, 0, v54
	v_cvt_f32_i32_e32 v54, v54
	v_ldexp_f32 v58, v58, v59
	v_ldexp_f32 v55, v55, v59
	v_add_f32_e32 v59, -1.0, v58
	v_add_f32_e32 v60, 1.0, v58
	v_add_f32_e32 v61, 1.0, v59
	v_add_f32_e32 v62, -1.0, v60
	v_sub_f32_e32 v61, v58, v61
	v_sub_f32_e32 v58, v58, v62
	v_mul_f32_e32 v62, 0x3f317218, v54
	v_add_f32_e32 v61, v55, v61
	v_add_f32_e32 v55, v55, v58
	v_fma_f32 v58, v54, s66, -v62
	v_add_f32_e32 v63, v59, v61
	v_add_f32_e32 v64, v60, v55
	v_fmac_f32_e32 v58, 0xb102e308, v54
	v_sub_f32_e32 v54, v59, v63
	v_sub_f32_e32 v59, v60, v64
	v_rcp_f32_e32 v60, v64
	v_add_f32_e32 v65, v62, v58
	v_add_f32_e32 v55, v55, v59
	v_sub_f32_e32 v59, v65, v62
	v_sub_f32_e32 v58, v58, v59
	v_mul_f32_e32 v59, v63, v60
	v_add_f32_e32 v54, v61, v54
	v_mul_f32_e32 v61, v64, v59
	v_fma_f32 v62, v59, v64, -v61
	v_fmac_f32_e32 v62, v59, v55
	v_add_f32_e32 v77, v61, v62
	v_sub_f32_e32 v78, v63, v77
	v_sub_f32_e32 v61, v77, v61
	v_sub_f32_e32 v63, v63, v78
	v_sub_f32_e32 v61, v61, v62
	v_sub_f32_e32 v62, v63, v77
	v_add_f32_e32 v54, v54, v62
	v_add_f32_e32 v54, v61, v54
	v_add_f32_e32 v61, v78, v54
	v_mul_f32_e32 v62, v60, v61
	v_sub_f32_e32 v63, v78, v61
	v_mul_f32_e32 v77, v64, v62
	v_add_f32_e32 v54, v54, v63
	v_add_f32_e32 v63, v59, v62
	v_fma_f32 v64, v62, v64, -v77
	v_sub_f32_e32 v59, v63, v59
	v_fmac_f32_e32 v64, v62, v55
	v_sub_f32_e32 v55, v62, v59
	v_add_f32_e32 v59, v77, v64
	v_sub_f32_e32 v62, v59, v77
	v_sub_f32_e32 v77, v61, v59
	v_sub_f32_e32 v61, v61, v77
	v_sub_f32_e32 v59, v61, v59
	v_sub_f32_e32 v62, v62, v64
	v_add_f32_e32 v54, v54, v59
	v_add_f32_e32 v54, v62, v54
	v_add_f32_e32 v54, v77, v54
	v_mul_f32_e32 v54, v60, v54
	v_add_f32_e32 v54, v55, v54
	v_add_f32_e32 v55, v63, v54
	v_mul_f32_e32 v59, v55, v55
	v_fmamk_f32 v62, v59, 0x3e9b6dac, v75
	v_sub_f32_e32 v60, v55, v63
	v_ldexp_f32 v61, v55, 1
	v_mul_f32_e32 v55, v55, v59
	v_fmaak_f32 v59, v59, v62, 0x3f2aaada
	v_mul_f32_e32 v55, v55, v59
	v_add_f32_e32 v59, v61, v55
	v_sub_f32_e32 v54, v54, v60
	v_sub_f32_e32 v60, v59, v61
	v_ldexp_f32 v54, v54, 1
	v_sub_f32_e32 v55, v55, v60
	v_add_f32_e32 v54, v54, v55
	v_add_f32_e32 v55, v59, v54
	v_sub_f32_e32 v59, v55, v59
	v_add_f32_e32 v60, v65, v55
	v_sub_f32_e32 v54, v54, v59
	v_sub_f32_e32 v59, v60, v65
	v_sub_f32_e32 v61, v60, v59
	v_sub_f32_e32 v55, v55, v59
	v_add_f32_e32 v59, v58, v54
	v_sub_f32_e32 v61, v65, v61
	v_sub_f32_e32 v62, v59, v58
	v_add_f32_e32 v55, v55, v61
	v_sub_f32_e32 v61, v59, v62
	v_sub_f32_e32 v54, v54, v62
	v_sub_f32_e32 v58, v58, v61
	v_add_f32_e32 v55, v59, v55
	v_add_f32_e32 v54, v54, v58
	v_add_f32_e32 v58, v60, v55
	v_sub_f32_e32 v59, v58, v60
	v_sub_f32_e32 v55, v55, v59
	v_add_f32_e32 v54, v54, v55
	v_add_f32_e32 v54, v58, v54
	v_cmp_neq_f32_e32 vcc, s64, v57
	s_nop 1
	v_cndmask_b32_e32 v54, v76, v54, vcc
	v_cmp_lt_f32_e64 vcc, |v57|, s67
	s_nop 1
	v_cndmask_b32_e32 v54, v54, v57, vcc
	v_sub_f32_e32 v54, v56, v54
	global_store_dword v[34:35], v54, off offset:16
	v_add_f32_e32 v40, s81, v40
	v_mul_f32_e64 v41, |v40|, s30
	v_fma_f32 v54, |v40|, s30, -v41
	v_rndne_f32_e32 v55, v41
	v_fma_f32 v54, |v40|, s31, v54
	v_sub_f32_e32 v41, v41, v55
	v_add_f32_e32 v41, v41, v54
	v_cvt_i32_f32_e32 v55, v55
	v_exp_f32_e32 v41, v41
	v_cmp_ngt_f32_e64 vcc, |v40|, s34
	v_min_f32_e32 v54, 0, v40
	v_ldexp_f32 v41, v41, v55
	v_cndmask_b32_e32 v41, 0, v41, vcc
	v_cmp_nlt_f32_e64 vcc, |v40|, s35
	s_nop 1
	v_cndmask_b32_e32 v55, v76, v41, vcc
	v_add_f32_e32 v56, 1.0, v55
	v_add_f32_e32 v57, -1.0, v56
	v_frexp_mant_f32_e32 v58, v56
	v_cvt_f64_f32_e32 v[40:41], v56
	v_sub_f32_e32 v59, v57, v56
	v_frexp_exp_i32_f64_e32 v40, v[40:41]
	v_cmp_gt_f32_e32 vcc, s65, v58
	v_sub_f32_e32 v57, v55, v57
	v_add_f32_e32 v41, 1.0, v59
	v_subbrev_co_u32_e32 v40, vcc, 0, v40, vcc
	v_add_f32_e32 v41, v57, v41
	v_sub_u32_e32 v57, 0, v40
	v_cvt_f32_i32_e32 v40, v40
	v_ldexp_f32 v56, v56, v57
	v_ldexp_f32 v41, v41, v57
	v_add_f32_e32 v57, -1.0, v56
	v_add_f32_e32 v58, 1.0, v56
	v_add_f32_e32 v59, 1.0, v57
	v_add_f32_e32 v60, -1.0, v58
	v_sub_f32_e32 v59, v56, v59
	v_sub_f32_e32 v56, v56, v60
	v_mul_f32_e32 v60, 0x3f317218, v40
	v_add_f32_e32 v59, v41, v59
	v_add_f32_e32 v41, v41, v56
	v_fma_f32 v56, v40, s66, -v60
	v_add_f32_e32 v61, v57, v59
	v_add_f32_e32 v62, v58, v41
	v_fmac_f32_e32 v56, 0xb102e308, v40
	v_sub_f32_e32 v40, v57, v61
	v_sub_f32_e32 v57, v58, v62
	v_rcp_f32_e32 v58, v62
	v_add_f32_e32 v63, v60, v56
	v_add_f32_e32 v41, v41, v57
	v_sub_f32_e32 v57, v63, v60
	v_sub_f32_e32 v56, v56, v57
	v_mul_f32_e32 v57, v61, v58
	v_add_f32_e32 v40, v59, v40
	v_mul_f32_e32 v59, v62, v57
	v_fma_f32 v60, v57, v62, -v59
	v_fmac_f32_e32 v60, v57, v41
	v_add_f32_e32 v64, v59, v60
	v_sub_f32_e32 v65, v61, v64
	v_sub_f32_e32 v59, v64, v59
	v_sub_f32_e32 v61, v61, v65
	v_sub_f32_e32 v59, v59, v60
	v_sub_f32_e32 v60, v61, v64
	v_add_f32_e32 v40, v40, v60
	v_add_f32_e32 v40, v59, v40
	v_add_f32_e32 v59, v65, v40
	v_mul_f32_e32 v60, v58, v59
	v_sub_f32_e32 v61, v65, v59
	v_mul_f32_e32 v64, v62, v60
	v_add_f32_e32 v40, v40, v61
	v_add_f32_e32 v61, v57, v60
	v_fma_f32 v62, v60, v62, -v64
	v_sub_f32_e32 v57, v61, v57
	v_fmac_f32_e32 v62, v60, v41
	v_sub_f32_e32 v41, v60, v57
	v_add_f32_e32 v57, v64, v62
	v_sub_f32_e32 v60, v57, v64
	v_sub_f32_e32 v64, v59, v57
	v_sub_f32_e32 v59, v59, v64
	v_sub_f32_e32 v57, v59, v57
	v_sub_f32_e32 v60, v60, v62
	v_add_f32_e32 v40, v40, v57
	v_add_f32_e32 v40, v60, v40
	v_add_f32_e32 v40, v64, v40
	v_mul_f32_e32 v40, v58, v40
	v_add_f32_e32 v40, v41, v40
	v_add_f32_e32 v41, v61, v40
	v_mul_f32_e32 v57, v41, v41
	v_fmamk_f32 v60, v57, 0x3e9b6dac, v75
	v_sub_f32_e32 v58, v41, v61
	v_ldexp_f32 v59, v41, 1
	v_mul_f32_e32 v41, v41, v57
	v_fmaak_f32 v57, v57, v60, 0x3f2aaada
	v_mul_f32_e32 v41, v41, v57
	v_add_f32_e32 v57, v59, v41
	v_sub_f32_e32 v40, v40, v58
	v_sub_f32_e32 v58, v57, v59
	v_ldexp_f32 v40, v40, 1
	v_sub_f32_e32 v41, v41, v58
	v_add_f32_e32 v40, v40, v41
	v_add_f32_e32 v41, v57, v40
	v_sub_f32_e32 v57, v41, v57
	v_add_f32_e32 v58, v63, v41
	v_sub_f32_e32 v40, v40, v57
	v_sub_f32_e32 v57, v58, v63
	v_sub_f32_e32 v59, v58, v57
	v_sub_f32_e32 v41, v41, v57
	v_add_f32_e32 v57, v56, v40
	v_sub_f32_e32 v59, v63, v59
	v_sub_f32_e32 v60, v57, v56
	v_add_f32_e32 v41, v41, v59
	v_sub_f32_e32 v59, v57, v60
	v_sub_f32_e32 v40, v40, v60
	v_sub_f32_e32 v56, v56, v59
	v_add_f32_e32 v41, v57, v41
	v_add_f32_e32 v40, v40, v56
	v_add_f32_e32 v56, v58, v41
	v_sub_f32_e32 v57, v56, v58
	v_sub_f32_e32 v41, v41, v57
	v_add_f32_e32 v40, v40, v41
	v_add_f32_e32 v40, v56, v40
	v_cmp_neq_f32_e32 vcc, s64, v55
	s_nop 1
	v_cndmask_b32_e32 v40, v76, v40, vcc
	v_cmp_lt_f32_e64 vcc, |v55|, s67
	s_nop 1
	v_cndmask_b32_e32 v40, v40, v55, vcc
	v_sub_f32_e32 v40, v54, v40
	global_store_dword v[34:35], v40, off offset:20
	v_add_f32_e32 v38, s82, v38
	v_mul_f32_e64 v39, |v38|, s30
	v_fma_f32 v40, |v38|, s30, -v39
	v_rndne_f32_e32 v41, v39
	v_fma_f32 v40, |v38|, s31, v40
	v_sub_f32_e32 v39, v39, v41
	v_add_f32_e32 v39, v39, v40
	v_cvt_i32_f32_e32 v41, v41
	v_exp_f32_e32 v39, v39
	v_cmp_ngt_f32_e64 vcc, |v38|, s34
	v_min_f32_e32 v40, 0, v38
	v_ldexp_f32 v39, v39, v41
	v_cndmask_b32_e32 v39, 0, v39, vcc
	v_cmp_nlt_f32_e64 vcc, |v38|, s35
	s_nop 1
	v_cndmask_b32_e32 v41, v76, v39, vcc
	v_add_f32_e32 v54, 1.0, v41
	v_add_f32_e32 v55, -1.0, v54
	v_frexp_mant_f32_e32 v56, v54
	v_cvt_f64_f32_e32 v[38:39], v54
	v_sub_f32_e32 v57, v55, v54
	v_frexp_exp_i32_f64_e32 v38, v[38:39]
	v_cmp_gt_f32_e32 vcc, s65, v56
	v_sub_f32_e32 v55, v41, v55
	v_add_f32_e32 v39, 1.0, v57
	v_subbrev_co_u32_e32 v38, vcc, 0, v38, vcc
	v_add_f32_e32 v39, v55, v39
	v_sub_u32_e32 v55, 0, v38
	v_cvt_f32_i32_e32 v38, v38
	v_ldexp_f32 v54, v54, v55
	v_ldexp_f32 v39, v39, v55
	v_add_f32_e32 v55, -1.0, v54
	v_add_f32_e32 v56, 1.0, v54
	v_add_f32_e32 v57, 1.0, v55
	v_add_f32_e32 v58, -1.0, v56
	v_sub_f32_e32 v57, v54, v57
	v_sub_f32_e32 v54, v54, v58
	v_mul_f32_e32 v58, 0x3f317218, v38
	v_add_f32_e32 v57, v39, v57
	v_add_f32_e32 v39, v39, v54
	v_fma_f32 v54, v38, s66, -v58
	v_add_f32_e32 v59, v55, v57
	v_add_f32_e32 v60, v56, v39
	v_fmac_f32_e32 v54, 0xb102e308, v38
	v_sub_f32_e32 v38, v55, v59
	v_sub_f32_e32 v55, v56, v60
	v_rcp_f32_e32 v56, v60
	v_add_f32_e32 v61, v58, v54
	v_add_f32_e32 v39, v39, v55
	v_sub_f32_e32 v55, v61, v58
	v_sub_f32_e32 v54, v54, v55
	v_mul_f32_e32 v55, v59, v56
	v_add_f32_e32 v38, v57, v38
	v_mul_f32_e32 v57, v60, v55
	v_fma_f32 v58, v55, v60, -v57
	v_fmac_f32_e32 v58, v55, v39
	v_add_f32_e32 v62, v57, v58
	v_sub_f32_e32 v63, v59, v62
	v_sub_f32_e32 v57, v62, v57
	v_sub_f32_e32 v59, v59, v63
	v_sub_f32_e32 v57, v57, v58
	v_sub_f32_e32 v58, v59, v62
	v_add_f32_e32 v38, v38, v58
	v_add_f32_e32 v38, v57, v38
	v_add_f32_e32 v57, v63, v38
	v_mul_f32_e32 v58, v56, v57
	v_sub_f32_e32 v59, v63, v57
	v_mul_f32_e32 v62, v60, v58
	v_add_f32_e32 v38, v38, v59
	v_add_f32_e32 v59, v55, v58
	v_fma_f32 v60, v58, v60, -v62
	v_sub_f32_e32 v55, v59, v55
	v_fmac_f32_e32 v60, v58, v39
	v_sub_f32_e32 v39, v58, v55
	v_add_f32_e32 v55, v62, v60
	v_sub_f32_e32 v58, v55, v62
	v_sub_f32_e32 v62, v57, v55
	v_sub_f32_e32 v57, v57, v62
	v_sub_f32_e32 v55, v57, v55
	v_sub_f32_e32 v58, v58, v60
	v_add_f32_e32 v38, v38, v55
	v_add_f32_e32 v38, v58, v38
	v_add_f32_e32 v38, v62, v38
	v_mul_f32_e32 v38, v56, v38
	v_add_f32_e32 v38, v39, v38
	v_add_f32_e32 v39, v59, v38
	v_mul_f32_e32 v55, v39, v39
	v_fmamk_f32 v58, v55, 0x3e9b6dac, v75
	v_sub_f32_e32 v56, v39, v59
	v_ldexp_f32 v57, v39, 1
	v_mul_f32_e32 v39, v39, v55
	v_fmaak_f32 v55, v55, v58, 0x3f2aaada
	v_mul_f32_e32 v39, v39, v55
	v_add_f32_e32 v55, v57, v39
	v_sub_f32_e32 v38, v38, v56
	v_sub_f32_e32 v56, v55, v57
	v_ldexp_f32 v38, v38, 1
	v_sub_f32_e32 v39, v39, v56
	v_add_f32_e32 v38, v38, v39
	v_add_f32_e32 v39, v55, v38
	v_sub_f32_e32 v55, v39, v55
	v_add_f32_e32 v56, v61, v39
	v_sub_f32_e32 v38, v38, v55
	v_sub_f32_e32 v55, v56, v61
	v_sub_f32_e32 v57, v56, v55
	v_sub_f32_e32 v39, v39, v55
	v_add_f32_e32 v55, v54, v38
	v_sub_f32_e32 v57, v61, v57
	v_sub_f32_e32 v58, v55, v54
	v_add_f32_e32 v39, v39, v57
	v_sub_f32_e32 v57, v55, v58
	v_sub_f32_e32 v38, v38, v58
	v_sub_f32_e32 v54, v54, v57
	v_add_f32_e32 v39, v55, v39
	v_add_f32_e32 v38, v38, v54
	v_add_f32_e32 v54, v56, v39
	v_sub_f32_e32 v55, v54, v56
	v_sub_f32_e32 v39, v39, v55
	v_add_f32_e32 v38, v38, v39
	v_add_f32_e32 v38, v54, v38
	v_cmp_neq_f32_e32 vcc, s64, v41
	s_nop 1
	v_cndmask_b32_e32 v38, v76, v38, vcc
	v_cmp_lt_f32_e64 vcc, |v41|, s67
	s_nop 1
	v_cndmask_b32_e32 v38, v38, v41, vcc
	v_sub_f32_e32 v38, v40, v38
	global_store_dword v[34:35], v38, off offset:24
	v_add_f32_e32 v36, s83, v36
	v_mul_f32_e64 v37, |v36|, s30
	v_fma_f32 v38, |v36|, s30, -v37
	v_rndne_f32_e32 v39, v37
	v_fma_f32 v38, |v36|, s31, v38
	v_sub_f32_e32 v37, v37, v39
	v_add_f32_e32 v37, v37, v38
	v_cvt_i32_f32_e32 v39, v39
	v_exp_f32_e32 v37, v37
	v_cmp_ngt_f32_e64 vcc, |v36|, s34
	v_min_f32_e32 v38, 0, v36
	v_ldexp_f32 v37, v37, v39
	v_cndmask_b32_e32 v37, 0, v37, vcc
	v_cmp_nlt_f32_e64 vcc, |v36|, s35
	s_nop 1
	v_cndmask_b32_e32 v39, v76, v37, vcc
	v_add_f32_e32 v40, 1.0, v39
	v_add_f32_e32 v41, -1.0, v40
	v_frexp_mant_f32_e32 v54, v40
	v_cvt_f64_f32_e32 v[36:37], v40
	v_sub_f32_e32 v55, v41, v40
	v_frexp_exp_i32_f64_e32 v36, v[36:37]
	v_cmp_gt_f32_e32 vcc, s65, v54
	v_sub_f32_e32 v41, v39, v41
	v_add_f32_e32 v37, 1.0, v55
	v_subbrev_co_u32_e32 v36, vcc, 0, v36, vcc
	v_add_f32_e32 v37, v41, v37
	v_sub_u32_e32 v41, 0, v36
	v_cvt_f32_i32_e32 v36, v36
	v_ldexp_f32 v40, v40, v41
	v_ldexp_f32 v37, v37, v41
	v_add_f32_e32 v41, -1.0, v40
	v_add_f32_e32 v54, 1.0, v40
	v_add_f32_e32 v55, 1.0, v41
	v_add_f32_e32 v56, -1.0, v54
	v_sub_f32_e32 v55, v40, v55
	v_sub_f32_e32 v40, v40, v56
	v_mul_f32_e32 v56, 0x3f317218, v36
	v_add_f32_e32 v55, v37, v55
	v_add_f32_e32 v37, v37, v40
	v_fma_f32 v40, v36, s66, -v56
	v_add_f32_e32 v57, v41, v55
	v_add_f32_e32 v58, v54, v37
	v_fmac_f32_e32 v40, 0xb102e308, v36
	v_sub_f32_e32 v36, v41, v57
	v_sub_f32_e32 v41, v54, v58
	v_rcp_f32_e32 v54, v58
	v_add_f32_e32 v59, v56, v40
	v_add_f32_e32 v37, v37, v41
	v_sub_f32_e32 v41, v59, v56
	v_sub_f32_e32 v40, v40, v41
	v_mul_f32_e32 v41, v57, v54
	v_add_f32_e32 v36, v55, v36
	v_mul_f32_e32 v55, v58, v41
	v_fma_f32 v56, v41, v58, -v55
	v_fmac_f32_e32 v56, v41, v37
	v_add_f32_e32 v60, v55, v56
	v_sub_f32_e32 v61, v57, v60
	v_sub_f32_e32 v55, v60, v55
	v_sub_f32_e32 v57, v57, v61
	v_sub_f32_e32 v55, v55, v56
	v_sub_f32_e32 v56, v57, v60
	v_add_f32_e32 v36, v36, v56
	v_add_f32_e32 v36, v55, v36
	v_add_f32_e32 v55, v61, v36
	v_mul_f32_e32 v56, v54, v55
	v_sub_f32_e32 v57, v61, v55
	v_mul_f32_e32 v60, v58, v56
	v_add_f32_e32 v36, v36, v57
	v_add_f32_e32 v57, v41, v56
	v_fma_f32 v58, v56, v58, -v60
	v_sub_f32_e32 v41, v57, v41
	v_fmac_f32_e32 v58, v56, v37
	v_sub_f32_e32 v37, v56, v41
	v_add_f32_e32 v41, v60, v58
	v_sub_f32_e32 v56, v41, v60
	v_sub_f32_e32 v60, v55, v41
	v_sub_f32_e32 v55, v55, v60
	v_sub_f32_e32 v41, v55, v41
	v_sub_f32_e32 v56, v56, v58
	v_add_f32_e32 v36, v36, v41
	v_add_f32_e32 v36, v56, v36
	v_add_f32_e32 v36, v60, v36
	v_mul_f32_e32 v36, v54, v36
	v_add_f32_e32 v36, v37, v36
	v_add_f32_e32 v37, v57, v36
	v_mul_f32_e32 v41, v37, v37
	v_fmamk_f32 v56, v41, 0x3e9b6dac, v75
	v_sub_f32_e32 v54, v37, v57
	v_ldexp_f32 v55, v37, 1
	v_mul_f32_e32 v37, v37, v41
	v_fmaak_f32 v41, v41, v56, 0x3f2aaada
	v_mul_f32_e32 v37, v37, v41
	v_add_f32_e32 v41, v55, v37
	v_sub_f32_e32 v36, v36, v54
	v_sub_f32_e32 v54, v41, v55
	v_ldexp_f32 v36, v36, 1
	v_sub_f32_e32 v37, v37, v54
	v_add_f32_e32 v36, v36, v37
	v_add_f32_e32 v37, v41, v36
	v_sub_f32_e32 v41, v37, v41
	v_add_f32_e32 v54, v59, v37
	v_sub_f32_e32 v36, v36, v41
	v_sub_f32_e32 v41, v54, v59
	v_sub_f32_e32 v55, v54, v41
	v_sub_f32_e32 v37, v37, v41
	v_add_f32_e32 v41, v40, v36
	v_sub_f32_e32 v55, v59, v55
	v_sub_f32_e32 v56, v41, v40
	v_add_f32_e32 v37, v37, v55
	v_sub_f32_e32 v55, v41, v56
	v_sub_f32_e32 v36, v36, v56
	v_sub_f32_e32 v40, v40, v55
	v_add_f32_e32 v37, v41, v37
	v_add_f32_e32 v36, v36, v40
	v_add_f32_e32 v40, v54, v37
	v_sub_f32_e32 v41, v40, v54
	v_sub_f32_e32 v37, v37, v41
	v_add_f32_e32 v36, v36, v37
	v_add_f32_e32 v36, v40, v36
	v_cmp_neq_f32_e32 vcc, s64, v39
	s_nop 1
	v_cndmask_b32_e32 v36, v76, v36, vcc
	v_cmp_lt_f32_e64 vcc, |v39|, s67
	s_nop 1
	v_cndmask_b32_e32 v36, v36, v39, vcc
	v_sub_f32_e32 v36, v38, v36
	global_store_dword v[34:35], v36, off offset:28
.LBB0_28:
	s_or_b64 exec, exec, s[26:27]
	s_and_saveexec_b64 s[26:27], s[4:5]
	s_cbranch_execz .LBB0_25
	v_pk_mul_f32 v[34:35], v[32:33], v[32:33]
	s_waitcnt lgkmcnt(0)
	v_pk_mul_f32 v[36:37], v[30:31], v[30:31]
	s_nop 0
	v_pk_mov_b32 v[38:39], v[36:37], v[34:35] op_sel:[1,0]
	v_mov_b32_e32 v37, v35
	v_pk_add_f32 v[34:35], v[38:39], v[36:37]
	v_pk_mul_f32 v[36:37], v[28:29], v[28:29]
	v_pk_mul_f32 v[38:39], v[26:27], v[26:27]
	v_pk_add_f32 v[34:35], v[34:35], v[34:35] op_sel:[0,1] op_sel_hi:[1,0]
	v_pk_mov_b32 v[40:41], v[38:39], v[36:37] op_sel:[1,0]
	v_mov_b32_e32 v39, v37
	v_pk_add_f32 v[36:37], v[40:41], v[38:39]
	v_mul_f32_e32 v38, v18, v18
	v_mul_f32_e32 v39, v19, v19
	v_pk_add_f32 v[36:37], v[36:37], v[36:37] op_sel:[0,1] op_sel_hi:[1,0]
	v_mov_b32_e32 v35, v38
	v_mov_b32_e32 v37, v39
	v_pk_add_f32 v[34:35], v[34:35], v[36:37]
	v_mul_f32_e32 v36, v23, v23
	v_mul_f32_e32 v38, v25, v25
	v_mul_f32_e32 v40, v20, v20
	v_mul_f32_e32 v41, v21, v21
	v_pk_fma_f32 v[36:37], v[22:23], v[22:23], v[36:37] op_sel_hi:[1,1,0]
	v_pk_fma_f32 v[38:39], v[24:25], v[24:25], v[38:39] op_sel_hi:[1,1,0]
	v_mov_b32_e32 v37, v40
	v_mov_b32_e32 v39, v41
	v_pk_add_f32 v[36:37], v[36:37], v[38:39]
	s_nop 0
	v_pk_add_f32 v[34:35], v[34:35], v[36:37]
	v_lshl_add_u64 v[36:37], s[74:75], 0, v[48:49]
	v_add_f32_e32 v34, v34, v35
	ds_bpermute_b32 v35, v66, v34
	s_waitcnt lgkmcnt(0)
	v_add_f32_e32 v34, v34, v35
	ds_bpermute_b32 v35, v67, v34
	s_waitcnt lgkmcnt(0)
	v_add_f32_e32 v34, v34, v35
	ds_bpermute_b32 v35, v68, v34
	s_waitcnt lgkmcnt(0)
	v_add_f32_e32 v34, v34, v35
	ds_bpermute_b32 v35, v69, v34
	s_waitcnt lgkmcnt(0)
	v_add_f32_e32 v34, v34, v35
	ds_bpermute_b32 v35, v70, v34
	s_waitcnt lgkmcnt(0)
	v_add_f32_e32 v34, v34, v35
	ds_bpermute_b32 v35, v71, v34
	s_waitcnt lgkmcnt(0)
	v_add_f32_e32 v34, v34, v35
	v_fmamk_f32 v34, v34, 0x3a800000, v74
	v_mul_f32_e32 v35, 0x4b800000, v34
	v_cmp_gt_f32_e32 vcc, s28, v34
	s_nop 1
	v_cndmask_b32_e32 v34, v34, v35, vcc
	v_rsq_f32_e32 v34, v34
	s_nop 0
	v_mul_f32_e32 v35, 0x45800000, v34
	v_cndmask_b32_e32 v38, v34, v35, vcc
	v_pk_mul_f32 v[30:31], v[30:31], v[38:39] op_sel_hi:[1,0]
	v_pk_mul_f32 v[32:33], v[32:33], v[38:39] op_sel_hi:[1,0]
	v_pk_mul_f32 v[34:35], v[2:3], v[30:31]
	v_add_co_u32_e32 v30, vcc, s29, v36
	v_pk_mul_f32 v[32:33], v[4:5], v[32:33]
	s_nop 0
	v_addc_co_u32_e32 v31, vcc, 0, v37, vcc
	v_pk_mul_f32 v[36:37], v[26:27], v[38:39] op_sel_hi:[1,0]
	v_pk_mul_f32 v[26:27], v[28:29], v[38:39] op_sel_hi:[1,0]
	v_cvt_pk_bf16_f32 v40, v34, v35
	v_cvt_pk_bf16_f32 v41, v32, v33
	global_store_dwordx2 v[30:31], v[40:41], off
	v_pk_mul_f32 v[26:27], v[8:9], v[26:27]
	v_pk_mul_f32 v[28:29], v[6:7], v[36:37]
	v_pk_mul_f32 v[18:19], v[18:19], v[38:39] op_sel_hi:[1,0]
	v_cvt_pk_bf16_f32 v36, v28, v29
	v_cvt_pk_bf16_f32 v37, v26, v27
	global_store_dwordx2 v[30:31], v[36:37], off offset:512
	v_pk_mul_f32 v[36:37], v[22:23], v[38:39] op_sel_hi:[1,0]
	v_pk_mul_f32 v[22:23], v[24:25], v[38:39] op_sel_hi:[1,0]
	v_pk_mul_f32 v[24:25], v[10:11], v[36:37]
	v_pk_mul_f32 v[22:23], v[12:13], v[22:23]
	v_cvt_pk_bf16_f32 v36, v24, v25
	v_pk_mul_f32 v[20:21], v[20:21], v[38:39] op_sel_hi:[1,0]
	v_cvt_pk_bf16_f32 v37, v22, v23
	global_store_dwordx2 v[30:31], v[36:37], off offset:1024
	v_pk_mul_f32 v[20:21], v[16:17], v[20:21]
	v_pk_mul_f32 v[36:37], v[14:15], v[18:19]
	s_nop 0
	v_cvt_pk_bf16_f32 v18, v36, v37
	v_cvt_pk_bf16_f32 v19, v20, v21
	ds_read_b128 v[38:41], v1
	ds_read_b128 v[54:57], v1 offset:1024
	global_store_dwordx2 v[30:31], v[18:19], off offset:1536
	ds_read_b128 v[78:81], v1 offset:21504
	s_waitcnt lgkmcnt(2)
	v_mul_f32_e32 v39, v35, v39
	v_fmac_f32_e32 v39, v34, v38
	v_mul_f32_e32 v38, v33, v41
	v_fmac_f32_e32 v38, v32, v40
	v_add_f32_e32 v38, v39, v38
	s_waitcnt lgkmcnt(1)
	v_mul_f32_e32 v55, v29, v55
	v_add_f32_e32 v58, 0, v38
	v_fmac_f32_e32 v55, v28, v54
	v_mul_f32_e32 v54, v27, v57
	ds_read_b128 v[38:41], v1 offset:2048
	v_fmac_f32_e32 v54, v26, v56
	v_add_f32_e32 v54, v55, v54
	v_add_f32_e32 v58, v58, v54
	ds_read_b128 v[54:57], v1 offset:3072
	s_waitcnt lgkmcnt(1)
	v_mul_f32_e32 v39, v25, v39
	v_fmac_f32_e32 v39, v24, v38
	v_mul_f32_e32 v38, v23, v41
	v_fmac_f32_e32 v38, v22, v40
	v_add_f32_e32 v38, v39, v38
	s_waitcnt lgkmcnt(0)
	v_mul_f32_e32 v39, v37, v55
	v_mul_f32_e32 v40, v21, v57
	v_fmac_f32_e32 v39, v36, v54
	v_fmac_f32_e32 v40, v20, v56
	v_add_f32_e32 v38, v58, v38
	v_add_f32_e32 v39, v39, v40
	v_add_f32_e32 v54, v38, v39
	ds_bpermute_b32 v55, v66, v54
	ds_read_b128 v[38:41], v1 offset:4096
	v_mul_f32_e32 v77, v27, v81
	v_fmac_f32_e32 v77, v26, v80
	s_waitcnt lgkmcnt(1)
	v_add_f32_e32 v58, v54, v55
	ds_read_b128 v[54:57], v1 offset:5120
	s_waitcnt lgkmcnt(1)
	v_mul_f32_e32 v39, v35, v39
	v_fmac_f32_e32 v39, v34, v38
	v_mul_f32_e32 v38, v33, v41
	v_fmac_f32_e32 v38, v32, v40
	v_add_f32_e32 v38, v39, v38
	s_waitcnt lgkmcnt(0)
	v_mul_f32_e32 v55, v29, v55
	v_add_f32_e32 v60, 0, v38
	v_fmac_f32_e32 v55, v28, v54
	v_mul_f32_e32 v54, v27, v57
	ds_read_b128 v[38:41], v1 offset:6144
	v_fmac_f32_e32 v54, v26, v56
	v_add_f32_e32 v54, v55, v54
	v_add_f32_e32 v60, v60, v54
	ds_read_b128 v[54:57], v1 offset:7168
	s_waitcnt lgkmcnt(1)
	v_mul_f32_e32 v39, v25, v39
	v_fmac_f32_e32 v39, v24, v38
	v_mul_f32_e32 v38, v23, v41
	v_fmac_f32_e32 v38, v22, v40
	v_add_f32_e32 v38, v39, v38
	s_waitcnt lgkmcnt(0)
	v_mul_f32_e32 v39, v37, v55
	v_mul_f32_e32 v40, v21, v57
	ds_bpermute_b32 v59, v67, v58
	v_fmac_f32_e32 v39, v36, v54
	v_fmac_f32_e32 v40, v20, v56
	v_add_f32_e32 v38, v60, v38
	v_add_f32_e32 v39, v39, v40
	v_add_f32_e32 v38, v38, v39
	ds_bpermute_b32 v39, v66, v38
	s_waitcnt lgkmcnt(1)
	v_add_f32_e32 v40, v58, v59
	ds_bpermute_b32 v41, v68, v40
	s_waitcnt lgkmcnt(1)
	v_add_f32_e32 v54, v38, v39
	ds_bpermute_b32 v55, v67, v54
	s_waitcnt lgkmcnt(1)
	v_add_f32_e32 v58, v40, v41
	ds_read_b128 v[38:41], v1 offset:8192
	ds_bpermute_b32 v59, v69, v58
	s_waitcnt lgkmcnt(2)
	v_add_f32_e32 v60, v54, v55
	ds_read_b128 v[54:57], v1 offset:9216
	s_waitcnt lgkmcnt(2)
	v_mul_f32_e32 v39, v35, v39
	v_fmac_f32_e32 v39, v34, v38
	v_mul_f32_e32 v38, v33, v41
	v_fmac_f32_e32 v38, v32, v40
	v_add_f32_e32 v38, v39, v38
	s_waitcnt lgkmcnt(0)
	v_mul_f32_e32 v55, v29, v55
	v_add_f32_e32 v62, 0, v38
	v_fmac_f32_e32 v55, v28, v54
	v_mul_f32_e32 v54, v27, v57
	ds_read_b128 v[38:41], v1 offset:10240
	v_fmac_f32_e32 v54, v26, v56
	v_add_f32_e32 v54, v55, v54
	v_add_f32_e32 v62, v62, v54
	ds_read_b128 v[54:57], v1 offset:11264
	s_waitcnt lgkmcnt(1)
	v_mul_f32_e32 v39, v25, v39
	v_fmac_f32_e32 v39, v24, v38
	v_mul_f32_e32 v38, v23, v41
	v_fmac_f32_e32 v38, v22, v40
	v_add_f32_e32 v38, v39, v38
	s_waitcnt lgkmcnt(0)
	v_mul_f32_e32 v39, v37, v55
	v_mul_f32_e32 v40, v21, v57
	v_fmac_f32_e32 v39, v36, v54
	v_fmac_f32_e32 v40, v20, v56
	v_add_f32_e32 v38, v62, v38
	v_add_f32_e32 v39, v39, v40
	v_add_f32_e32 v38, v38, v39
	ds_bpermute_b32 v61, v68, v60
	ds_bpermute_b32 v39, v66, v38
	v_add_f32_e32 v40, v58, v59
	ds_bpermute_b32 v41, v70, v40
	ds_read_b128 v[54:57], v1 offset:12288
	s_waitcnt lgkmcnt(3)
	v_add_f32_e32 v58, v60, v61
	s_waitcnt lgkmcnt(2)
	v_add_f32_e32 v60, v38, v39
	ds_bpermute_b32 v59, v69, v58
	ds_bpermute_b32 v61, v67, v60
	s_waitcnt lgkmcnt(3)
	v_add_f32_e32 v38, v40, v41
	ds_bpermute_b32 v39, v71, v38
	s_waitcnt lgkmcnt(2)
	v_add_f32_e32 v40, v58, v59
	s_waitcnt lgkmcnt(1)
	v_add_f32_e32 v41, v60, v61
	ds_read_b128 v[58:61], v1 offset:13312
	v_mul_f32_e32 v55, v35, v55
	v_fmac_f32_e32 v55, v34, v54
	v_mul_f32_e32 v54, v33, v57
	v_fmac_f32_e32 v54, v32, v56
	v_add_f32_e32 v54, v55, v54
	s_waitcnt lgkmcnt(0)
	v_mul_f32_e32 v59, v29, v59
	v_add_f32_e32 v63, 0, v54
	v_fmac_f32_e32 v59, v28, v58
	v_mul_f32_e32 v58, v27, v61
	ds_read_b128 v[54:57], v1 offset:14336
	v_fmac_f32_e32 v58, v26, v60
	v_add_f32_e32 v58, v59, v58
	v_add_f32_e32 v63, v63, v58
	ds_read_b128 v[58:61], v1 offset:15360
	s_waitcnt lgkmcnt(1)
	v_mul_f32_e32 v55, v25, v55
	v_fmac_f32_e32 v55, v24, v54
	v_mul_f32_e32 v54, v23, v57
	v_fmac_f32_e32 v54, v22, v56
	v_add_f32_e32 v54, v55, v54
	s_waitcnt lgkmcnt(0)
	v_mul_f32_e32 v59, v37, v59
	v_add_f32_e32 v63, v63, v54
	v_fmac_f32_e32 v59, v36, v58
	v_mul_f32_e32 v58, v21, v61
	ds_read_b128 v[54:57], v1 offset:16384
	v_fmac_f32_e32 v58, v20, v60
	v_add_f32_e32 v58, v59, v58
	v_add_f32_e32 v63, v63, v58
	ds_read_b128 v[58:61], v1 offset:17408
	s_waitcnt lgkmcnt(1)
	v_mul_f32_e32 v55, v35, v55
	v_fmac_f32_e32 v55, v34, v54
	v_mul_f32_e32 v54, v33, v57
	v_fmac_f32_e32 v54, v32, v56
	v_add_f32_e32 v54, v55, v54
	s_waitcnt lgkmcnt(0)
	v_mul_f32_e32 v59, v29, v59
	v_add_f32_e32 v65, 0, v54
	v_fmac_f32_e32 v59, v28, v58
	v_mul_f32_e32 v58, v27, v61
	ds_read_b128 v[54:57], v1 offset:18432
	v_fmac_f32_e32 v58, v26, v60
	v_add_f32_e32 v58, v59, v58
	v_add_f32_e32 v65, v65, v58
	ds_read_b128 v[58:61], v1 offset:19456
	s_waitcnt lgkmcnt(1)
	v_mul_f32_e32 v55, v25, v55
	v_fmac_f32_e32 v55, v24, v54
	v_mul_f32_e32 v54, v23, v57
	v_fmac_f32_e32 v54, v22, v56
	v_add_f32_e32 v54, v55, v54
	s_waitcnt lgkmcnt(0)
	v_mul_f32_e32 v55, v37, v59
	v_mul_f32_e32 v56, v21, v61
	v_fmac_f32_e32 v55, v36, v58
	v_fmac_f32_e32 v56, v20, v60
	v_add_f32_e32 v54, v65, v54
	v_add_f32_e32 v55, v55, v56
	v_add_f32_e32 v54, v54, v55
	ds_bpermute_b32 v64, v66, v63
	ds_bpermute_b32 v55, v66, v54
	ds_bpermute_b32 v62, v68, v41
	ds_bpermute_b32 v56, v70, v40
	s_waitcnt lgkmcnt(3)
	v_add_f32_e32 v57, v63, v64
	s_waitcnt lgkmcnt(2)
	v_add_f32_e32 v54, v54, v55
	ds_bpermute_b32 v58, v67, v57
	ds_bpermute_b32 v55, v67, v54
	s_waitcnt lgkmcnt(3)
	v_add_f32_e32 v41, v41, v62
	ds_bpermute_b32 v59, v69, v41
	s_waitcnt lgkmcnt(3)
	v_add_f32_e32 v40, v40, v56
	s_waitcnt lgkmcnt(2)
	v_add_f32_e32 v57, v57, v58
	s_waitcnt lgkmcnt(1)
	v_add_f32_e32 v54, v54, v55
	ds_bpermute_b32 v58, v68, v57
	ds_bpermute_b32 v55, v68, v54
	s_waitcnt lgkmcnt(2)
	v_add_f32_e32 v41, v41, v59
	ds_read_b128 v[60:63], v1 offset:20480
	s_waitcnt lgkmcnt(2)
	v_add_f32_e32 v56, v57, v58
	s_waitcnt lgkmcnt(1)
	v_add_f32_e32 v54, v54, v55
	ds_bpermute_b32 v57, v69, v56
	ds_bpermute_b32 v59, v69, v54
	s_waitcnt lgkmcnt(2)
	v_mul_f32_e32 v61, v35, v61
	v_fmac_f32_e32 v61, v34, v60
	v_mul_f32_e32 v60, v33, v63
	s_waitcnt lgkmcnt(1)
	v_add_f32_e32 v56, v56, v57
	s_waitcnt lgkmcnt(0)
	v_add_f32_e32 v64, v54, v59
	ds_bpermute_b32 v57, v70, v56
	ds_bpermute_b32 v65, v70, v64
	v_fmac_f32_e32 v60, v32, v62
	v_add_f32_e32 v60, v61, v60
	ds_bpermute_b32 v58, v70, v41
	s_waitcnt lgkmcnt(2)
	v_add_f32_e32 v54, v56, v57
	s_waitcnt lgkmcnt(1)
	v_add_f32_e32 v56, v64, v65
	v_add_f32_e32 v64, 0, v60
	ds_read_b128 v[60:63], v1 offset:22528
	v_mul_f32_e32 v65, v29, v79
	v_fmac_f32_e32 v65, v28, v78
	ds_read_b128 v[78:81], v1 offset:23552
	v_add_f32_e32 v65, v65, v77
	s_waitcnt lgkmcnt(1)
	v_mul_f32_e32 v61, v25, v61
	v_fmac_f32_e32 v61, v24, v60
	v_mul_f32_e32 v60, v23, v63
	v_fmac_f32_e32 v60, v22, v62
	v_add_f32_e32 v64, v64, v65
	v_add_f32_e32 v60, v61, v60
	v_add_f32_e32 v64, v64, v60
	ds_read_b128 v[60:63], v1 offset:24576
	s_waitcnt lgkmcnt(1)
	v_mul_f32_e32 v65, v37, v79
	v_mul_f32_e32 v77, v21, v81
	v_fmac_f32_e32 v65, v36, v78
	v_fmac_f32_e32 v77, v20, v80
	ds_read_b128 v[78:81], v1 offset:25600
	s_waitcnt lgkmcnt(1)
	v_mul_f32_e32 v61, v35, v61
	v_fmac_f32_e32 v61, v34, v60
	v_mul_f32_e32 v60, v33, v63
	v_fmac_f32_e32 v60, v32, v62
	s_waitcnt lgkmcnt(0)
	v_mul_f32_e32 v79, v29, v79
	v_add_f32_e32 v60, v61, v60
	v_fmac_f32_e32 v79, v28, v78
	v_mul_f32_e32 v78, v27, v81
	v_add_f32_e32 v65, v65, v77
	v_add_f32_e32 v77, 0, v60
	ds_read_b128 v[60:63], v1 offset:26624
	v_fmac_f32_e32 v78, v26, v80
	v_add_f32_e32 v78, v79, v78
	v_add_f32_e32 v77, v77, v78
	ds_read_b128 v[78:81], v1 offset:27648
	s_waitcnt lgkmcnt(1)
	v_mul_f32_e32 v61, v25, v61
	v_fmac_f32_e32 v61, v24, v60
	v_mul_f32_e32 v60, v23, v63
	v_fmac_f32_e32 v60, v22, v62
	s_waitcnt lgkmcnt(0)
	v_mul_f32_e32 v79, v37, v79
	v_add_f32_e32 v60, v61, v60
	v_fmac_f32_e32 v79, v36, v78
	v_mul_f32_e32 v78, v21, v81
	v_add_f32_e32 v77, v77, v60
	v_fmac_f32_e32 v78, v20, v80
	ds_read_b128 v[60:63], v1 offset:28672
	v_add_f32_e32 v78, v79, v78
	v_add_f32_e32 v77, v77, v78
	ds_read_b128 v[78:81], v1 offset:29696
	v_add_f32_e32 v64, v64, v65
	s_waitcnt lgkmcnt(1)
	v_mul_f32_e32 v35, v35, v61
	v_mul_f32_e32 v33, v33, v63
	v_fmac_f32_e32 v35, v34, v60
	v_fmac_f32_e32 v33, v32, v62
	v_add_f32_e32 v32, v35, v33
	s_waitcnt lgkmcnt(0)
	v_mul_f32_e32 v29, v29, v79
	v_mul_f32_e32 v27, v27, v81
	v_add_f32_e32 v60, 0, v32
	v_fmac_f32_e32 v29, v28, v78
	ds_read_b128 v[32:35], v1 offset:30720
	v_fmac_f32_e32 v27, v26, v80
	v_add_f32_e32 v26, v29, v27
	v_add_f32_e32 v60, v60, v26
	ds_read_b128 v[26:29], v1 offset:31744
	s_waitcnt lgkmcnt(1)
	v_mul_f32_e32 v25, v25, v33
	v_mul_f32_e32 v23, v23, v35
	v_fmac_f32_e32 v25, v24, v32
	v_fmac_f32_e32 v23, v22, v34
	v_add_f32_e32 v22, v25, v23
	s_waitcnt lgkmcnt(0)
	v_mul_f32_e32 v23, v37, v27
	v_mul_f32_e32 v21, v21, v29
	v_fmac_f32_e32 v23, v36, v26
	v_fmac_f32_e32 v21, v20, v28
	v_add_f32_e32 v22, v60, v22
	v_add_f32_e32 v20, v23, v21
	v_add_f32_e32 v20, v22, v20
	ds_bpermute_b32 v65, v66, v64
	ds_bpermute_b32 v82, v66, v77
	ds_bpermute_b32 v21, v66, v20
	v_add_f32_e32 v41, v41, v58
	ds_bpermute_b32 v55, v71, v40
	s_waitcnt lgkmcnt(3)
	v_add_f32_e32 v22, v64, v65
	s_waitcnt lgkmcnt(2)
	v_add_f32_e32 v24, v77, v82
	s_waitcnt lgkmcnt(1)
	v_add_f32_e32 v20, v20, v21
	ds_bpermute_b32 v23, v67, v22
	ds_bpermute_b32 v25, v67, v24
	ds_bpermute_b32 v21, v67, v20
	ds_bpermute_b32 v58, v71, v41
	ds_bpermute_b32 v59, v71, v54
	s_waitcnt lgkmcnt(4)
	v_add_f32_e32 v22, v22, v23
	s_waitcnt lgkmcnt(3)
	v_add_f32_e32 v24, v24, v25
	s_waitcnt lgkmcnt(2)
	v_add_f32_e32 v20, v20, v21
	ds_bpermute_b32 v23, v68, v22
	ds_bpermute_b32 v25, v68, v24
	ds_bpermute_b32 v21, v68, v20
	ds_bpermute_b32 v57, v71, v56
	s_waitcnt lgkmcnt(3)
	v_add_f32_e32 v22, v22, v23
	s_waitcnt lgkmcnt(2)
	v_add_f32_e32 v24, v24, v25
	s_waitcnt lgkmcnt(1)
	v_add_f32_e32 v20, v20, v21
	ds_bpermute_b32 v23, v69, v22
	ds_bpermute_b32 v25, v69, v24
	ds_bpermute_b32 v21, v69, v20
	s_waitcnt lgkmcnt(2)
	v_add_f32_e32 v22, v22, v23
	s_waitcnt lgkmcnt(1)
	v_add_f32_e32 v26, v24, v25
	s_waitcnt lgkmcnt(0)
	v_add_f32_e32 v20, v20, v21
	ds_bpermute_b32 v23, v70, v22
	ds_bpermute_b32 v27, v70, v26
	ds_bpermute_b32 v21, v70, v20
	s_waitcnt lgkmcnt(2)
	v_add_f32_e32 v24, v22, v23
	s_waitcnt lgkmcnt(1)
	v_add_f32_e32 v22, v26, v27
	s_waitcnt lgkmcnt(0)
	v_add_f32_e32 v20, v20, v21
	ds_bpermute_b32 v25, v71, v24
	ds_bpermute_b32 v23, v71, v22
	ds_bpermute_b32 v21, v71, v20
	s_and_b64 exec, exec, s[2:3]
	s_cbranch_execz .LBB0_25
	v_readlane_b32 s36, v254, 5
	v_readlane_b32 s37, v254, 6
	v_lshl_add_u64 v[18:19], s[74:75], 0, v[46:47]
	v_add_f32_e32 v27, v38, v39
	v_add_co_u32_e32 v18, vcc, 0x26a8000, v18
	v_readlane_b32 s38, v254, 7
	s_nop 0
	v_addc_co_u32_e32 v19, vcc, 0, v19, vcc
	v_readlane_b32 s39, v254, 8
	s_waitcnt lgkmcnt(2)
	v_add_f32_e32 v24, v24, v25
	s_waitcnt lgkmcnt(1)
	v_add_f32_e32 v22, v22, v23
	s_waitcnt lgkmcnt(0)
	v_add_f32_e32 v20, v20, v21
	v_readlane_b32 s40, v254, 9
	v_readlane_b32 s41, v254, 10
	v_readlane_b32 s42, v254, 11
	v_readlane_b32 s43, v254, 12
	v_readlane_b32 s44, v254, 13
	v_readlane_b32 s45, v254, 14
	v_readlane_b32 s46, v254, 15
	v_readlane_b32 s47, v254, 16
	v_readlane_b32 s48, v254, 17
	v_readlane_b32 s49, v254, 18
	v_readlane_b32 s50, v254, 19
	v_readlane_b32 s51, v254, 20
	v_add_f32_e32 v26, s76, v27
	global_store_dword v[18:19], v26, off
	v_add_f32_e32 v27, v40, v55
	v_add_f32_e32 v26, s77, v27
	global_store_dword v[18:19], v26, off offset:4
	v_add_f32_e32 v27, v41, v58
	v_add_f32_e32 v26, s78, v27
	global_store_dword v[18:19], v26, off offset:8
	v_add_f32_e32 v27, v54, v59
	v_add_f32_e32 v26, s79, v27
	global_store_dword v[18:19], v26, off offset:12
	v_add_f32_e32 v27, v56, v57
	v_add_f32_e32 v26, s80, v27
	v_mul_f32_e64 v27, |v26|, s30
	v_fma_f32 v28, |v26|, s30, -v27
	v_rndne_f32_e32 v29, v27
	v_fma_f32 v28, |v26|, s31, v28
	v_sub_f32_e32 v27, v27, v29
	v_add_f32_e32 v27, v27, v28
	v_cvt_i32_f32_e32 v29, v29
	v_exp_f32_e32 v27, v27
	v_cmp_ngt_f32_e64 vcc, |v26|, s34
	v_min_f32_e32 v28, 0, v26
	v_ldexp_f32 v27, v27, v29
	v_cndmask_b32_e32 v27, 0, v27, vcc
	v_cmp_nlt_f32_e64 vcc, |v26|, s35
	s_nop 1
	v_cndmask_b32_e32 v29, v76, v27, vcc
	v_add_f32_e32 v30, 1.0, v29
	v_add_f32_e32 v31, -1.0, v30
	v_frexp_mant_f32_e32 v32, v30
	v_cvt_f64_f32_e32 v[26:27], v30
	v_sub_f32_e32 v33, v31, v30
	v_frexp_exp_i32_f64_e32 v26, v[26:27]
	v_cmp_gt_f32_e32 vcc, s65, v32
	v_sub_f32_e32 v31, v29, v31
	v_add_f32_e32 v27, 1.0, v33
	v_subbrev_co_u32_e32 v26, vcc, 0, v26, vcc
	v_add_f32_e32 v27, v31, v27
	v_sub_u32_e32 v31, 0, v26
	v_cvt_f32_i32_e32 v26, v26
	v_ldexp_f32 v30, v30, v31
	v_ldexp_f32 v27, v27, v31
	v_add_f32_e32 v31, -1.0, v30
	v_add_f32_e32 v32, 1.0, v30
	v_add_f32_e32 v33, 1.0, v31
	v_add_f32_e32 v34, -1.0, v32
	v_sub_f32_e32 v33, v30, v33
	v_sub_f32_e32 v30, v30, v34
	v_mul_f32_e32 v34, 0x3f317218, v26
	v_add_f32_e32 v33, v27, v33
	v_add_f32_e32 v27, v27, v30
	v_fma_f32 v30, v26, s66, -v34
	v_add_f32_e32 v35, v31, v33
	v_add_f32_e32 v36, v32, v27
	v_fmac_f32_e32 v30, 0xb102e308, v26
	v_sub_f32_e32 v26, v31, v35
	v_sub_f32_e32 v31, v32, v36
	v_rcp_f32_e32 v32, v36
	v_add_f32_e32 v37, v34, v30
	v_add_f32_e32 v27, v27, v31
	v_sub_f32_e32 v31, v37, v34
	v_sub_f32_e32 v30, v30, v31
	v_mul_f32_e32 v31, v35, v32
	v_add_f32_e32 v26, v33, v26
	v_mul_f32_e32 v33, v36, v31
	v_fma_f32 v34, v31, v36, -v33
	v_fmac_f32_e32 v34, v31, v27
	v_add_f32_e32 v38, v33, v34
	v_sub_f32_e32 v39, v35, v38
	v_sub_f32_e32 v33, v38, v33
	v_sub_f32_e32 v35, v35, v39
	v_sub_f32_e32 v33, v33, v34
	v_sub_f32_e32 v34, v35, v38
	v_add_f32_e32 v26, v26, v34
	v_add_f32_e32 v26, v33, v26
	v_add_f32_e32 v33, v39, v26
	v_mul_f32_e32 v34, v32, v33
	v_sub_f32_e32 v35, v39, v33
	v_mul_f32_e32 v38, v36, v34
	v_add_f32_e32 v26, v26, v35
	v_add_f32_e32 v35, v31, v34
	v_fma_f32 v36, v34, v36, -v38
	v_sub_f32_e32 v31, v35, v31
	v_fmac_f32_e32 v36, v34, v27
	v_sub_f32_e32 v27, v34, v31
	v_add_f32_e32 v31, v38, v36
	v_sub_f32_e32 v34, v31, v38
	v_sub_f32_e32 v38, v33, v31
	v_sub_f32_e32 v33, v33, v38
	v_sub_f32_e32 v31, v33, v31
	v_sub_f32_e32 v34, v34, v36
	v_add_f32_e32 v26, v26, v31
	v_add_f32_e32 v26, v34, v26
	v_add_f32_e32 v26, v38, v26
	v_mul_f32_e32 v26, v32, v26
	v_add_f32_e32 v26, v27, v26
	v_add_f32_e32 v27, v35, v26
	v_mul_f32_e32 v31, v27, v27
	v_fmamk_f32 v34, v31, 0x3e9b6dac, v75
	v_sub_f32_e32 v32, v27, v35
	v_ldexp_f32 v33, v27, 1
	v_mul_f32_e32 v27, v27, v31
	v_fmaak_f32 v31, v31, v34, 0x3f2aaada
	v_mul_f32_e32 v27, v27, v31
	v_add_f32_e32 v31, v33, v27
	v_sub_f32_e32 v26, v26, v32
	v_sub_f32_e32 v32, v31, v33
	v_ldexp_f32 v26, v26, 1
	v_sub_f32_e32 v27, v27, v32
	v_add_f32_e32 v26, v26, v27
	v_add_f32_e32 v27, v31, v26
	v_sub_f32_e32 v31, v27, v31
	v_add_f32_e32 v32, v37, v27
	v_sub_f32_e32 v26, v26, v31
	v_sub_f32_e32 v31, v32, v37
	v_sub_f32_e32 v33, v32, v31
	v_sub_f32_e32 v27, v27, v31
	v_add_f32_e32 v31, v30, v26
	v_sub_f32_e32 v33, v37, v33
	v_sub_f32_e32 v34, v31, v30
	v_add_f32_e32 v27, v27, v33
	v_sub_f32_e32 v33, v31, v34
	v_sub_f32_e32 v26, v26, v34
	v_sub_f32_e32 v30, v30, v33
	v_add_f32_e32 v27, v31, v27
	v_add_f32_e32 v26, v26, v30
	v_add_f32_e32 v30, v32, v27
	v_sub_f32_e32 v31, v30, v32
	v_sub_f32_e32 v27, v27, v31
	v_add_f32_e32 v26, v26, v27
	v_add_f32_e32 v26, v30, v26
	v_cmp_neq_f32_e32 vcc, s64, v29
	s_nop 1
	v_cndmask_b32_e32 v26, v76, v26, vcc
	v_cmp_lt_f32_e64 vcc, |v29|, s67
	s_nop 1
	v_cndmask_b32_e32 v26, v26, v29, vcc
	v_sub_f32_e32 v26, v28, v26
	global_store_dword v[18:19], v26, off offset:16
	v_add_f32_e32 v24, s81, v24
	v_mul_f32_e64 v25, |v24|, s30
	v_fma_f32 v26, |v24|, s30, -v25
	v_rndne_f32_e32 v27, v25
	v_fma_f32 v26, |v24|, s31, v26
	v_sub_f32_e32 v25, v25, v27
	v_add_f32_e32 v25, v25, v26
	v_cvt_i32_f32_e32 v27, v27
	v_exp_f32_e32 v25, v25
	v_cmp_ngt_f32_e64 vcc, |v24|, s34
	v_min_f32_e32 v26, 0, v24
	v_ldexp_f32 v25, v25, v27
	v_cndmask_b32_e32 v25, 0, v25, vcc
	v_cmp_nlt_f32_e64 vcc, |v24|, s35
	s_nop 1
	v_cndmask_b32_e32 v27, v76, v25, vcc
	v_add_f32_e32 v28, 1.0, v27
	v_add_f32_e32 v29, -1.0, v28
	v_frexp_mant_f32_e32 v30, v28
	v_cvt_f64_f32_e32 v[24:25], v28
	v_sub_f32_e32 v31, v29, v28
	v_frexp_exp_i32_f64_e32 v24, v[24:25]
	v_cmp_gt_f32_e32 vcc, s65, v30
	v_sub_f32_e32 v29, v27, v29
	v_add_f32_e32 v25, 1.0, v31
	v_subbrev_co_u32_e32 v24, vcc, 0, v24, vcc
	v_add_f32_e32 v25, v29, v25
	v_sub_u32_e32 v29, 0, v24
	v_cvt_f32_i32_e32 v24, v24
	v_ldexp_f32 v28, v28, v29
	v_ldexp_f32 v25, v25, v29
	v_add_f32_e32 v29, -1.0, v28
	v_add_f32_e32 v30, 1.0, v28
	v_add_f32_e32 v31, 1.0, v29
	v_add_f32_e32 v32, -1.0, v30
	v_sub_f32_e32 v31, v28, v31
	v_sub_f32_e32 v28, v28, v32
	v_mul_f32_e32 v32, 0x3f317218, v24
	v_add_f32_e32 v31, v25, v31
	v_add_f32_e32 v25, v25, v28
	v_fma_f32 v28, v24, s66, -v32
	v_add_f32_e32 v33, v29, v31
	v_add_f32_e32 v34, v30, v25
	v_fmac_f32_e32 v28, 0xb102e308, v24
	v_sub_f32_e32 v24, v29, v33
	v_sub_f32_e32 v29, v30, v34
	v_rcp_f32_e32 v30, v34
	v_add_f32_e32 v35, v32, v28
	v_add_f32_e32 v25, v25, v29
	v_sub_f32_e32 v29, v35, v32
	v_sub_f32_e32 v28, v28, v29
	v_mul_f32_e32 v29, v33, v30
	v_add_f32_e32 v24, v31, v24
	v_mul_f32_e32 v31, v34, v29
	v_fma_f32 v32, v29, v34, -v31
	v_fmac_f32_e32 v32, v29, v25
	v_add_f32_e32 v36, v31, v32
	v_sub_f32_e32 v37, v33, v36
	v_sub_f32_e32 v31, v36, v31
	v_sub_f32_e32 v33, v33, v37
	v_sub_f32_e32 v31, v31, v32
	v_sub_f32_e32 v32, v33, v36
	v_add_f32_e32 v24, v24, v32
	v_add_f32_e32 v24, v31, v24
	v_add_f32_e32 v31, v37, v24
	v_mul_f32_e32 v32, v30, v31
	v_sub_f32_e32 v33, v37, v31
	v_mul_f32_e32 v36, v34, v32
	v_add_f32_e32 v24, v24, v33
	v_add_f32_e32 v33, v29, v32
	v_fma_f32 v34, v32, v34, -v36
	v_sub_f32_e32 v29, v33, v29
	v_fmac_f32_e32 v34, v32, v25
	v_sub_f32_e32 v25, v32, v29
	v_add_f32_e32 v29, v36, v34
	v_sub_f32_e32 v32, v29, v36
	v_sub_f32_e32 v36, v31, v29
	v_sub_f32_e32 v31, v31, v36
	v_sub_f32_e32 v29, v31, v29
	v_sub_f32_e32 v32, v32, v34
	v_add_f32_e32 v24, v24, v29
	v_add_f32_e32 v24, v32, v24
	v_add_f32_e32 v24, v36, v24
	v_mul_f32_e32 v24, v30, v24
	v_add_f32_e32 v24, v25, v24
	v_add_f32_e32 v25, v33, v24
	v_mul_f32_e32 v29, v25, v25
	v_fmamk_f32 v32, v29, 0x3e9b6dac, v75
	v_sub_f32_e32 v30, v25, v33
	v_ldexp_f32 v31, v25, 1
	v_mul_f32_e32 v25, v25, v29
	v_fmaak_f32 v29, v29, v32, 0x3f2aaada
	v_mul_f32_e32 v25, v25, v29
	v_add_f32_e32 v29, v31, v25
	v_sub_f32_e32 v24, v24, v30
	v_sub_f32_e32 v30, v29, v31
	v_ldexp_f32 v24, v24, 1
	v_sub_f32_e32 v25, v25, v30
	v_add_f32_e32 v24, v24, v25
	v_add_f32_e32 v25, v29, v24
	v_sub_f32_e32 v29, v25, v29
	v_add_f32_e32 v30, v35, v25
	v_sub_f32_e32 v24, v24, v29
	v_sub_f32_e32 v29, v30, v35
	v_sub_f32_e32 v31, v30, v29
	v_sub_f32_e32 v25, v25, v29
	v_add_f32_e32 v29, v28, v24
	v_sub_f32_e32 v31, v35, v31
	v_sub_f32_e32 v32, v29, v28
	v_add_f32_e32 v25, v25, v31
	v_sub_f32_e32 v31, v29, v32
	v_sub_f32_e32 v24, v24, v32
	v_sub_f32_e32 v28, v28, v31
	v_add_f32_e32 v25, v29, v25
	v_add_f32_e32 v24, v24, v28
	v_add_f32_e32 v28, v30, v25
	v_sub_f32_e32 v29, v28, v30
	v_sub_f32_e32 v25, v25, v29
	v_add_f32_e32 v24, v24, v25
	v_add_f32_e32 v24, v28, v24
	v_cmp_neq_f32_e32 vcc, s64, v27
	s_nop 1
	v_cndmask_b32_e32 v24, v76, v24, vcc
	v_cmp_lt_f32_e64 vcc, |v27|, s67
	s_nop 1
	v_cndmask_b32_e32 v24, v24, v27, vcc
	v_sub_f32_e32 v24, v26, v24
	global_store_dword v[18:19], v24, off offset:20
	v_add_f32_e32 v22, s82, v22
	v_mul_f32_e64 v23, |v22|, s30
	v_fma_f32 v24, |v22|, s30, -v23
	v_rndne_f32_e32 v25, v23
	v_fma_f32 v24, |v22|, s31, v24
	v_sub_f32_e32 v23, v23, v25
	v_add_f32_e32 v23, v23, v24
	v_cvt_i32_f32_e32 v25, v25
	v_exp_f32_e32 v23, v23
	v_cmp_ngt_f32_e64 vcc, |v22|, s34
	v_min_f32_e32 v24, 0, v22
	v_ldexp_f32 v23, v23, v25
	v_cndmask_b32_e32 v23, 0, v23, vcc
	v_cmp_nlt_f32_e64 vcc, |v22|, s35
	s_nop 1
	v_cndmask_b32_e32 v25, v76, v23, vcc
	v_add_f32_e32 v26, 1.0, v25
	v_add_f32_e32 v27, -1.0, v26
	v_frexp_mant_f32_e32 v28, v26
	v_cvt_f64_f32_e32 v[22:23], v26
	v_sub_f32_e32 v29, v27, v26
	v_frexp_exp_i32_f64_e32 v22, v[22:23]
	v_cmp_gt_f32_e32 vcc, s65, v28
	v_sub_f32_e32 v27, v25, v27
	v_add_f32_e32 v23, 1.0, v29
	v_subbrev_co_u32_e32 v22, vcc, 0, v22, vcc
	v_add_f32_e32 v23, v27, v23
	v_sub_u32_e32 v27, 0, v22
	v_cvt_f32_i32_e32 v22, v22
	v_ldexp_f32 v26, v26, v27
	v_ldexp_f32 v23, v23, v27
	v_add_f32_e32 v27, -1.0, v26
	v_add_f32_e32 v28, 1.0, v26
	v_add_f32_e32 v29, 1.0, v27
	v_add_f32_e32 v30, -1.0, v28
	v_sub_f32_e32 v29, v26, v29
	v_sub_f32_e32 v26, v26, v30
	v_mul_f32_e32 v30, 0x3f317218, v22
	v_add_f32_e32 v29, v23, v29
	v_add_f32_e32 v23, v23, v26
	v_fma_f32 v26, v22, s66, -v30
	v_add_f32_e32 v31, v27, v29
	v_add_f32_e32 v32, v28, v23
	v_fmac_f32_e32 v26, 0xb102e308, v22
	v_sub_f32_e32 v22, v27, v31
	v_sub_f32_e32 v27, v28, v32
	v_rcp_f32_e32 v28, v32
	v_add_f32_e32 v33, v30, v26
	v_add_f32_e32 v23, v23, v27
	v_sub_f32_e32 v27, v33, v30
	v_sub_f32_e32 v26, v26, v27
	v_mul_f32_e32 v27, v31, v28
	v_add_f32_e32 v22, v29, v22
	v_mul_f32_e32 v29, v32, v27
	v_fma_f32 v30, v27, v32, -v29
	v_fmac_f32_e32 v30, v27, v23
	v_add_f32_e32 v34, v29, v30
	v_sub_f32_e32 v35, v31, v34
	v_sub_f32_e32 v29, v34, v29
	v_sub_f32_e32 v31, v31, v35
	v_sub_f32_e32 v29, v29, v30
	v_sub_f32_e32 v30, v31, v34
	v_add_f32_e32 v22, v22, v30
	v_add_f32_e32 v22, v29, v22
	v_add_f32_e32 v29, v35, v22
	v_mul_f32_e32 v30, v28, v29
	v_sub_f32_e32 v31, v35, v29
	v_mul_f32_e32 v34, v32, v30
	v_add_f32_e32 v22, v22, v31
	v_add_f32_e32 v31, v27, v30
	v_fma_f32 v32, v30, v32, -v34
	v_sub_f32_e32 v27, v31, v27
	v_fmac_f32_e32 v32, v30, v23
	v_sub_f32_e32 v23, v30, v27
	v_add_f32_e32 v27, v34, v32
	v_sub_f32_e32 v30, v27, v34
	v_sub_f32_e32 v34, v29, v27
	v_sub_f32_e32 v29, v29, v34
	v_sub_f32_e32 v27, v29, v27
	v_sub_f32_e32 v30, v30, v32
	v_add_f32_e32 v22, v22, v27
	v_add_f32_e32 v22, v30, v22
	v_add_f32_e32 v22, v34, v22
	v_mul_f32_e32 v22, v28, v22
	v_add_f32_e32 v22, v23, v22
	v_add_f32_e32 v23, v31, v22
	v_mul_f32_e32 v27, v23, v23
	v_fmamk_f32 v30, v27, 0x3e9b6dac, v75
	v_sub_f32_e32 v28, v23, v31
	v_ldexp_f32 v29, v23, 1
	v_mul_f32_e32 v23, v23, v27
	v_fmaak_f32 v27, v27, v30, 0x3f2aaada
	v_mul_f32_e32 v23, v23, v27
	v_add_f32_e32 v27, v29, v23
	v_sub_f32_e32 v22, v22, v28
	v_sub_f32_e32 v28, v27, v29
	v_ldexp_f32 v22, v22, 1
	v_sub_f32_e32 v23, v23, v28
	v_add_f32_e32 v22, v22, v23
	v_add_f32_e32 v23, v27, v22
	v_sub_f32_e32 v27, v23, v27
	v_add_f32_e32 v28, v33, v23
	v_sub_f32_e32 v22, v22, v27
	v_sub_f32_e32 v27, v28, v33
	v_sub_f32_e32 v29, v28, v27
	v_sub_f32_e32 v23, v23, v27
	v_add_f32_e32 v27, v26, v22
	v_sub_f32_e32 v29, v33, v29
	v_sub_f32_e32 v30, v27, v26
	v_add_f32_e32 v23, v23, v29
	v_sub_f32_e32 v29, v27, v30
	v_sub_f32_e32 v22, v22, v30
	v_sub_f32_e32 v26, v26, v29
	v_add_f32_e32 v23, v27, v23
	v_add_f32_e32 v22, v22, v26
	v_add_f32_e32 v26, v28, v23
	v_sub_f32_e32 v27, v26, v28
	v_sub_f32_e32 v23, v23, v27
	v_add_f32_e32 v22, v22, v23
	v_add_f32_e32 v22, v26, v22
	v_cmp_neq_f32_e32 vcc, s64, v25
	s_nop 1
	v_cndmask_b32_e32 v22, v76, v22, vcc
	v_cmp_lt_f32_e64 vcc, |v25|, s67
	s_nop 1
	v_cndmask_b32_e32 v22, v22, v25, vcc
	v_sub_f32_e32 v22, v24, v22
	global_store_dword v[18:19], v22, off offset:24
	v_add_f32_e32 v20, s83, v20
	v_mul_f32_e64 v21, |v20|, s30
	v_fma_f32 v22, |v20|, s30, -v21
	v_rndne_f32_e32 v23, v21
	v_fma_f32 v22, |v20|, s31, v22
	v_sub_f32_e32 v21, v21, v23
	v_add_f32_e32 v21, v21, v22
	v_cvt_i32_f32_e32 v23, v23
	v_exp_f32_e32 v21, v21
	v_cmp_ngt_f32_e64 vcc, |v20|, s34
	v_min_f32_e32 v22, 0, v20
	v_ldexp_f32 v21, v21, v23
	v_cndmask_b32_e32 v21, 0, v21, vcc
	v_cmp_nlt_f32_e64 vcc, |v20|, s35
	s_nop 1
	v_cndmask_b32_e32 v23, v76, v21, vcc
	v_add_f32_e32 v24, 1.0, v23
	v_add_f32_e32 v25, -1.0, v24
	v_frexp_mant_f32_e32 v26, v24
	v_cvt_f64_f32_e32 v[20:21], v24
	v_sub_f32_e32 v27, v25, v24
	v_frexp_exp_i32_f64_e32 v20, v[20:21]
	v_cmp_gt_f32_e32 vcc, s65, v26
	v_sub_f32_e32 v25, v23, v25
	v_add_f32_e32 v21, 1.0, v27
	v_subbrev_co_u32_e32 v20, vcc, 0, v20, vcc
	v_add_f32_e32 v21, v25, v21
	v_sub_u32_e32 v25, 0, v20
	v_cvt_f32_i32_e32 v20, v20
	v_ldexp_f32 v24, v24, v25
	v_ldexp_f32 v21, v21, v25
	v_add_f32_e32 v25, -1.0, v24
	v_add_f32_e32 v26, 1.0, v24
	v_add_f32_e32 v27, 1.0, v25
	v_add_f32_e32 v28, -1.0, v26
	v_sub_f32_e32 v27, v24, v27
	v_sub_f32_e32 v24, v24, v28
	v_mul_f32_e32 v28, 0x3f317218, v20
	v_add_f32_e32 v27, v21, v27
	v_add_f32_e32 v21, v21, v24
	v_fma_f32 v24, v20, s66, -v28
	v_add_f32_e32 v29, v25, v27
	v_add_f32_e32 v30, v26, v21
	v_fmac_f32_e32 v24, 0xb102e308, v20
	v_sub_f32_e32 v20, v25, v29
	v_sub_f32_e32 v25, v26, v30
	v_rcp_f32_e32 v26, v30
	v_add_f32_e32 v31, v28, v24
	v_add_f32_e32 v21, v21, v25
	v_sub_f32_e32 v25, v31, v28
	v_sub_f32_e32 v24, v24, v25
	v_mul_f32_e32 v25, v29, v26
	v_add_f32_e32 v20, v27, v20
	v_mul_f32_e32 v27, v30, v25
	v_fma_f32 v28, v25, v30, -v27
	v_fmac_f32_e32 v28, v25, v21
	v_add_f32_e32 v32, v27, v28
	v_sub_f32_e32 v33, v29, v32
	v_sub_f32_e32 v27, v32, v27
	v_sub_f32_e32 v29, v29, v33
	v_sub_f32_e32 v27, v27, v28
	v_sub_f32_e32 v28, v29, v32
	v_add_f32_e32 v20, v20, v28
	v_add_f32_e32 v20, v27, v20
	v_add_f32_e32 v27, v33, v20
	v_mul_f32_e32 v28, v26, v27
	v_sub_f32_e32 v29, v33, v27
	v_mul_f32_e32 v32, v30, v28
	v_add_f32_e32 v20, v20, v29
	v_add_f32_e32 v29, v25, v28
	v_fma_f32 v30, v28, v30, -v32
	v_sub_f32_e32 v25, v29, v25
	v_fmac_f32_e32 v30, v28, v21
	v_sub_f32_e32 v21, v28, v25
	v_add_f32_e32 v25, v32, v30
	v_sub_f32_e32 v28, v25, v32
	v_sub_f32_e32 v32, v27, v25
	v_sub_f32_e32 v27, v27, v32
	v_sub_f32_e32 v25, v27, v25
	v_sub_f32_e32 v28, v28, v30
	v_add_f32_e32 v20, v20, v25
	v_add_f32_e32 v20, v28, v20
	v_add_f32_e32 v20, v32, v20
	v_mul_f32_e32 v20, v26, v20
	v_add_f32_e32 v20, v21, v20
	v_add_f32_e32 v21, v29, v20
	v_mul_f32_e32 v25, v21, v21
	v_fmamk_f32 v28, v25, 0x3e9b6dac, v75
	v_sub_f32_e32 v26, v21, v29
	v_ldexp_f32 v27, v21, 1
	v_mul_f32_e32 v21, v21, v25
	v_fmaak_f32 v25, v25, v28, 0x3f2aaada
	v_mul_f32_e32 v21, v21, v25
	v_add_f32_e32 v25, v27, v21
	v_sub_f32_e32 v20, v20, v26
	v_sub_f32_e32 v26, v25, v27
	v_ldexp_f32 v20, v20, 1
	v_sub_f32_e32 v21, v21, v26
	v_add_f32_e32 v20, v20, v21
	v_add_f32_e32 v21, v25, v20
	v_sub_f32_e32 v25, v21, v25
	v_add_f32_e32 v26, v31, v21
	v_sub_f32_e32 v20, v20, v25
	v_sub_f32_e32 v25, v26, v31
	v_sub_f32_e32 v27, v26, v25
	v_sub_f32_e32 v21, v21, v25
	v_add_f32_e32 v25, v24, v20
	v_sub_f32_e32 v27, v31, v27
	v_sub_f32_e32 v28, v25, v24
	v_add_f32_e32 v21, v21, v27
	v_sub_f32_e32 v27, v25, v28
	v_sub_f32_e32 v20, v20, v28
	v_sub_f32_e32 v24, v24, v27
	v_add_f32_e32 v21, v25, v21
	v_add_f32_e32 v20, v20, v24
	v_add_f32_e32 v24, v26, v21
	v_sub_f32_e32 v25, v24, v26
	v_sub_f32_e32 v21, v21, v25
	v_add_f32_e32 v20, v20, v21
	v_add_f32_e32 v20, v24, v20
	v_cmp_neq_f32_e32 vcc, s64, v23
	s_nop 1
	v_cndmask_b32_e32 v20, v76, v20, vcc
	v_cmp_lt_f32_e64 vcc, |v23|, s67
	s_nop 1
	v_cndmask_b32_e32 v20, v20, v23, vcc
	v_sub_f32_e32 v20, v22, v20
	global_store_dword v[18:19], v20, off offset:28
	s_branch .LBB0_25

.LBB0_216:
	s_or_b32 s9, s22, 1
	s_and_b32 s2, s22, 0x1ff
	s_cmp_lg_u32 s2, 0
	s_cselect_b64 s[10:11], -1, 0
	s_cmp_eq_u32 s2, 0
	s_cselect_b64 s[2:3], -1, 0
	s_and_b64 vcc, s[2:3], exec
	s_cselect_b32 s2, s9, s22
	s_lshl_b32 s2, s2, 2
	v_mov_b32_e32 v50, 0
	v_mov_b32_e32 v52, 0
	v_mov_b32_e32 v53, 0
	s_cbranch_vccnz .LBB0_218
	s_ashr_i32 s3, s2, 31
	s_lshl_b64 s[4:5], s[2:3], 12
	v_lshl_add_u64 v[26:27], v[22:23], 0, s[4:5]
	v_add_co_u32_e32 v26, vcc, 0xffffd000, v26
	s_nop 1
	v_addc_co_u32_e32 v27, vcc, -1, v27, vcc
	global_load_dwordx2 v[52:53], v[26:27], off

.LBB0_762:
	ds_read_b128 v[138:141], v147
	ds_read_b128 v[186:189], v147 offset:1024
	ds_read_b128 v[190:193], v147 offset:2048
	ds_read_b128 v[194:197], v147 offset:3072
	s_add_u32 s58, s56, 0xfffc0080
	s_addc_u32 s59, s57, -1
	s_cmp_eq_u32 s47, 12
	s_cselect_b32 s61, s21, s59
	s_cselect_b32 s60, s22, s58
	s_cselect_b32 s59, s23, s46
	s_cselect_b32 s58, s41, s43
	v_lshl_add_u64 v[142:143], s[56:57], 0, v[130:131]
	s_add_i32 m0, s51, 0xc000
	ds_read_b128 v[198:201], v158
	ds_read_b128 v[202:205], v158 offset:1024
	ds_read_b128 v[206:209], v158 offset:2048
	ds_read_b128 v[210:213], v158 offset:3072
	ds_read_b128 v[214:217], v158 offset:4096
	ds_read_b128 v[218:221], v158 offset:5120
	ds_read_b128 v[222:225], v158 offset:6144
	ds_read_b128 v[226:229], v158 offset:7168
	global_load_lds_dwordx4 v[142:143], off
	v_lshl_add_u64 v[142:143], s[56:57], 0, v[132:133]
	s_add_i32 m0, s51, 0xe000
	s_nop 0
	global_load_lds_dwordx4 v[142:143], off
	s_waitcnt lgkmcnt(8)
	s_barrier
	s_waitcnt lgkmcnt(0)
	s_setprio 1
	s_waitcnt lgkmcnt(0)
	v_mfma_f32_16x16x32_bf16 v[126:129], v[138:141], v[198:201], v[126:129]
	v_mfma_f32_16x16x32_bf16 v[122:125], v[190:193], v[198:201], v[122:125]
	v_mfma_f32_16x16x32_bf16 v[110:113], v[138:141], v[206:209], v[110:113]
	v_mfma_f32_16x16x32_bf16 v[106:109], v[190:193], v[206:209], v[106:109]
	v_mfma_f32_16x16x32_bf16 v[94:97], v[138:141], v[214:217], v[94:97]
	v_mfma_f32_16x16x32_bf16 v[90:93], v[190:193], v[214:217], v[90:93]
	v_mfma_f32_16x16x32_bf16 v[78:81], v[138:141], v[222:225], v[78:81]
	v_mfma_f32_16x16x32_bf16 v[74:77], v[190:193], v[222:225], v[74:77]
	v_mfma_f32_16x16x32_bf16 v[126:129], v[186:189], v[202:205], v[126:129]
	v_mfma_f32_16x16x32_bf16 v[122:125], v[194:197], v[202:205], v[122:125]
	v_mfma_f32_16x16x32_bf16 v[110:113], v[186:189], v[210:213], v[110:113]
	v_mfma_f32_16x16x32_bf16 v[106:109], v[194:197], v[210:213], v[106:109]
	v_mfma_f32_16x16x32_bf16 v[94:97], v[186:189], v[218:221], v[94:97]
	v_mfma_f32_16x16x32_bf16 v[90:93], v[194:197], v[218:221], v[90:93]
	v_mfma_f32_16x16x32_bf16 v[78:81], v[186:189], v[226:229], v[78:81]
	v_mfma_f32_16x16x32_bf16 v[74:77], v[194:197], v[226:229], v[74:77]
	s_setprio 0
	s_barrier
	s_add_i32 s74, s72, s64
	v_lshl_add_u64 v[142:143], s[58:59], 0, v[152:153]
	s_mov_b32 m0, s74
	ds_read_b128 v[230:233], v159
	ds_read_b128 v[234:237], v159 offset:1024
	ds_read_b128 v[238:241], v159 offset:2048
	ds_read_b128 v[242:245], v159 offset:3072
	global_load_lds_dwordx4 v[142:143], off
	v_lshl_add_u64 v[246:247], s[58:59], 0, v[156:157]
	s_add_i32 m0, s74, 0x2000
	s_nop 0
	global_load_lds_dwordx4 v[246:247], off
	s_barrier
	s_waitcnt lgkmcnt(0)
	s_setprio 1
	s_waitcnt lgkmcnt(0)
	v_mfma_f32_16x16x32_bf16 v[118:121], v[230:233], v[198:201], v[118:121]
	v_mfma_f32_16x16x32_bf16 v[114:117], v[238:241], v[198:201], v[114:117]
	v_mfma_f32_16x16x32_bf16 v[102:105], v[230:233], v[206:209], v[102:105]
	v_mfma_f32_16x16x32_bf16 v[98:101], v[238:241], v[206:209], v[98:101]
	v_mfma_f32_16x16x32_bf16 v[86:89], v[230:233], v[214:217], v[86:89]
	v_mfma_f32_16x16x32_bf16 v[82:85], v[238:241], v[214:217], v[82:85]
	v_mfma_f32_16x16x32_bf16 v[70:73], v[230:233], v[222:225], v[70:73]
	v_mfma_f32_16x16x32_bf16 v[66:69], v[238:241], v[222:225], v[66:69]
	v_mfma_f32_16x16x32_bf16 v[118:121], v[234:237], v[202:205], v[118:121]
	v_mfma_f32_16x16x32_bf16 v[114:117], v[242:245], v[202:205], v[114:117]
	v_mfma_f32_16x16x32_bf16 v[102:105], v[234:237], v[210:213], v[102:105]
	v_mfma_f32_16x16x32_bf16 v[98:101], v[242:245], v[210:213], v[98:101]
	v_mfma_f32_16x16x32_bf16 v[86:89], v[234:237], v[218:221], v[86:89]
	v_mfma_f32_16x16x32_bf16 v[82:85], v[242:245], v[218:221], v[82:85]
	v_mfma_f32_16x16x32_bf16 v[70:73], v[234:237], v[226:229], v[70:73]
	v_mfma_f32_16x16x32_bf16 v[66:69], v[242:245], v[226:229], v[66:69]
	s_setprio 0
	s_mov_b32 m0, s51
	v_lshl_add_u64 v[248:249], s[60:61], 0, v[150:151]
	s_barrier
	ds_read_b128 v[198:201], v158 offset:16384
	ds_read_b128 v[202:205], v158 offset:17408
	ds_read_b128 v[206:209], v158 offset:18432
	ds_read_b128 v[210:213], v158 offset:19456
	ds_read_b128 v[214:217], v158 offset:20480
	ds_read_b128 v[218:221], v158 offset:21504
	ds_read_b128 v[222:225], v158 offset:22528
	ds_read_b128 v[226:229], v158 offset:23552
	global_load_lds_dwordx4 v[248:249], off
	v_lshl_add_u64 v[250:251], s[60:61], 0, v[154:155]
	s_mov_b32 m0, s65
	s_nop 0
	global_load_lds_dwordx4 v[250:251], off
	s_barrier
	s_waitcnt lgkmcnt(0)
	s_setprio 1
	s_waitcnt lgkmcnt(0)
	v_mfma_f32_16x16x32_bf16 v[62:65], v[138:141], v[198:201], v[62:65]
	v_mfma_f32_16x16x32_bf16 v[58:61], v[190:193], v[198:201], v[58:61]
	v_mfma_f32_16x16x32_bf16 v[46:49], v[138:141], v[206:209], v[46:49]
	v_mfma_f32_16x16x32_bf16 v[42:45], v[190:193], v[206:209], v[42:45]
	v_mfma_f32_16x16x32_bf16 v[30:33], v[138:141], v[214:217], v[30:33]
	v_mfma_f32_16x16x32_bf16 v[26:29], v[190:193], v[214:217], v[26:29]
	v_mfma_f32_16x16x32_bf16 v[14:17], v[138:141], v[222:225], v[14:17]
	v_mfma_f32_16x16x32_bf16 v[10:13], v[190:193], v[222:225], v[10:13]
	v_mfma_f32_16x16x32_bf16 v[62:65], v[186:189], v[202:205], v[62:65]
	v_mfma_f32_16x16x32_bf16 v[58:61], v[194:197], v[202:205], v[58:61]
	v_mfma_f32_16x16x32_bf16 v[46:49], v[186:189], v[210:213], v[46:49]
	v_mfma_f32_16x16x32_bf16 v[42:45], v[194:197], v[210:213], v[42:45]
	v_mfma_f32_16x16x32_bf16 v[30:33], v[186:189], v[218:221], v[30:33]
	v_mfma_f32_16x16x32_bf16 v[26:29], v[194:197], v[218:221], v[26:29]
	v_mfma_f32_16x16x32_bf16 v[14:17], v[186:189], v[226:229], v[14:17]
	v_mfma_f32_16x16x32_bf16 v[10:13], v[194:197], v[226:229], v[10:13]
	s_setprio 0
	s_barrier
	s_add_u32 s74, s58, 0x40000
	s_addc_u32 s75, s59, 0
	s_add_i32 s76, s73, s64
	v_lshl_add_u64 v[138:139], s[74:75], 0, v[152:153]
	s_mov_b32 m0, s76
	s_nop 0
	global_load_lds_dwordx4 v[138:139], off
	v_lshl_add_u64 v[138:139], s[74:75], 0, v[156:157]
	s_add_i32 m0, s76, 0x2000
	s_nop 0
	global_load_lds_dwordx4 v[138:139], off
	s_waitcnt vmcnt(6)
	s_barrier
	s_setprio 1
	v_mfma_f32_16x16x32_bf16 v[54:57], v[230:233], v[198:201], v[54:57]
	v_mfma_f32_16x16x32_bf16 v[50:53], v[238:241], v[198:201], v[50:53]
	v_mfma_f32_16x16x32_bf16 v[38:41], v[230:233], v[206:209], v[38:41]
	v_mfma_f32_16x16x32_bf16 v[34:37], v[238:241], v[206:209], v[34:37]
	v_mfma_f32_16x16x32_bf16 v[22:25], v[230:233], v[214:217], v[22:25]
	v_mfma_f32_16x16x32_bf16 v[18:21], v[238:241], v[214:217], v[18:21]
	v_mfma_f32_16x16x32_bf16 v[6:9], v[230:233], v[222:225], v[6:9]
	v_mfma_f32_16x16x32_bf16 v[2:5], v[238:241], v[222:225], v[2:5]
	v_mfma_f32_16x16x32_bf16 v[54:57], v[234:237], v[202:205], v[54:57]
	v_mfma_f32_16x16x32_bf16 v[50:53], v[242:245], v[202:205], v[50:53]
	v_mfma_f32_16x16x32_bf16 v[38:41], v[234:237], v[210:213], v[38:41]
	v_mfma_f32_16x16x32_bf16 v[34:37], v[242:245], v[210:213], v[34:37]
	v_mfma_f32_16x16x32_bf16 v[22:25], v[234:237], v[218:221], v[22:25]
	v_mfma_f32_16x16x32_bf16 v[18:21], v[242:245], v[218:221], v[18:21]
	v_mfma_f32_16x16x32_bf16 v[6:9], v[234:237], v[226:229], v[6:9]
	v_mfma_f32_16x16x32_bf16 v[2:5], v[242:245], v[226:229], v[2:5]
	s_setprio 0
	s_add_i32 s74, 0, 0x18000
	v_add_u32_e32 v169, s74, v145
	s_barrier
	ds_read_b128 v[138:141], v169
	ds_read_b128 v[186:189], v169 offset:1024
	ds_read_b128 v[190:193], v169 offset:2048
	ds_read_b128 v[194:197], v169 offset:3072
	s_add_u32 s60, s60, 0x40000
	s_addc_u32 s61, s61, 0
	s_mov_b32 m0, s66
	v_lshl_add_u64 v[230:231], s[60:61], 0, v[150:151]
	ds_read_b128 v[198:201], v158 offset:32768
	ds_read_b128 v[202:205], v158 offset:33792
	ds_read_b128 v[206:209], v158 offset:34816
	ds_read_b128 v[210:213], v158 offset:35840
	ds_read_b128 v[214:217], v158 offset:36864
	ds_read_b128 v[218:221], v158 offset:37888
	ds_read_b128 v[222:225], v158 offset:38912
	ds_read_b128 v[226:229], v158 offset:39936
	global_load_lds_dwordx4 v[230:231], off
	v_lshl_add_u64 v[230:231], s[60:61], 0, v[154:155]
	s_mov_b32 m0, s67
	s_nop 0
	global_load_lds_dwordx4 v[230:231], off
	s_waitcnt lgkmcnt(8)
	s_barrier
	s_waitcnt lgkmcnt(0)
	s_setprio 1
	s_waitcnt lgkmcnt(0)
	v_mfma_f32_16x16x32_bf16 v[126:129], v[138:141], v[198:201], v[126:129]
	v_mfma_f32_16x16x32_bf16 v[122:125], v[190:193], v[198:201], v[122:125]
	v_mfma_f32_16x16x32_bf16 v[110:113], v[138:141], v[206:209], v[110:113]
	v_mfma_f32_16x16x32_bf16 v[106:109], v[190:193], v[206:209], v[106:109]
	v_mfma_f32_16x16x32_bf16 v[94:97], v[138:141], v[214:217], v[94:97]
	v_mfma_f32_16x16x32_bf16 v[90:93], v[190:193], v[214:217], v[90:93]
	v_mfma_f32_16x16x32_bf16 v[78:81], v[138:141], v[222:225], v[78:81]
	v_mfma_f32_16x16x32_bf16 v[74:77], v[190:193], v[222:225], v[74:77]
	v_mfma_f32_16x16x32_bf16 v[126:129], v[186:189], v[202:205], v[126:129]
	v_mfma_f32_16x16x32_bf16 v[122:125], v[194:197], v[202:205], v[122:125]
	v_mfma_f32_16x16x32_bf16 v[110:113], v[186:189], v[210:213], v[110:113]
	v_mfma_f32_16x16x32_bf16 v[106:109], v[194:197], v[210:213], v[106:109]
	v_mfma_f32_16x16x32_bf16 v[94:97], v[186:189], v[218:221], v[94:97]
	v_mfma_f32_16x16x32_bf16 v[90:93], v[194:197], v[218:221], v[90:93]
	v_mfma_f32_16x16x32_bf16 v[78:81], v[186:189], v[226:229], v[78:81]
	v_mfma_f32_16x16x32_bf16 v[74:77], v[194:197], v[226:229], v[74:77]
	s_setprio 0
	s_barrier
	s_add_i32 s60, 0, 0x1c000
	s_add_i32 s61, s74, s64
	v_add_u32_e32 v169, s60, v145
	v_lshl_add_u64 v[142:143], v[142:143], 0, s[12:13]
	s_mov_b32 m0, s61
	ds_read_b128 v[230:233], v169
	ds_read_b128 v[234:237], v169 offset:1024
	ds_read_b128 v[238:241], v169 offset:2048
	ds_read_b128 v[242:245], v169 offset:3072
	global_load_lds_dwordx4 v[142:143], off
	v_lshl_add_u64 v[142:143], v[246:247], 0, s[12:13]
	s_add_i32 m0, s61, 0x2000
	s_nop 0
	global_load_lds_dwordx4 v[142:143], off
	s_barrier
	s_waitcnt lgkmcnt(0)
	s_setprio 1
	s_waitcnt lgkmcnt(0)
	v_mfma_f32_16x16x32_bf16 v[118:121], v[230:233], v[198:201], v[118:121]
	v_mfma_f32_16x16x32_bf16 v[114:117], v[238:241], v[198:201], v[114:117]
	v_mfma_f32_16x16x32_bf16 v[102:105], v[230:233], v[206:209], v[102:105]
	v_mfma_f32_16x16x32_bf16 v[98:101], v[238:241], v[206:209], v[98:101]
	v_mfma_f32_16x16x32_bf16 v[86:89], v[230:233], v[214:217], v[86:89]
	v_mfma_f32_16x16x32_bf16 v[82:85], v[238:241], v[214:217], v[82:85]
	v_mfma_f32_16x16x32_bf16 v[70:73], v[230:233], v[222:225], v[70:73]
	v_mfma_f32_16x16x32_bf16 v[66:69], v[238:241], v[222:225], v[66:69]
	v_mfma_f32_16x16x32_bf16 v[118:121], v[234:237], v[202:205], v[118:121]
	v_mfma_f32_16x16x32_bf16 v[114:117], v[242:245], v[202:205], v[114:117]
	v_mfma_f32_16x16x32_bf16 v[102:105], v[234:237], v[210:213], v[102:105]
	v_mfma_f32_16x16x32_bf16 v[98:101], v[242:245], v[210:213], v[98:101]
	v_mfma_f32_16x16x32_bf16 v[86:89], v[234:237], v[218:221], v[86:89]
	v_mfma_f32_16x16x32_bf16 v[82:85], v[242:245], v[218:221], v[82:85]
	v_mfma_f32_16x16x32_bf16 v[70:73], v[234:237], v[226:229], v[70:73]
	v_mfma_f32_16x16x32_bf16 v[66:69], v[242:245], v[226:229], v[66:69]
	s_setprio 0
	s_mov_b32 m0, s69
	v_lshl_add_u64 v[142:143], v[248:249], 0, s[12:13]
	s_barrier
	ds_read_b128 v[198:201], v158 offset:49152
	ds_read_b128 v[202:205], v158 offset:50176
	ds_read_b128 v[206:209], v158 offset:51200
	ds_read_b128 v[210:213], v158 offset:52224
	ds_read_b128 v[214:217], v158 offset:53248
	ds_read_b128 v[218:221], v158 offset:54272
	ds_read_b128 v[222:225], v158 offset:55296
	ds_read_b128 v[226:229], v158 offset:56320
	global_load_lds_dwordx4 v[142:143], off
	v_lshl_add_u64 v[142:143], v[250:251], 0, s[12:13]
	s_mov_b32 m0, s70
	s_nop 0
	global_load_lds_dwordx4 v[142:143], off
	s_barrier
	s_waitcnt lgkmcnt(0)
	s_setprio 1
	s_waitcnt lgkmcnt(0)
	v_mfma_f32_16x16x32_bf16 v[62:65], v[138:141], v[198:201], v[62:65]
	v_mfma_f32_16x16x32_bf16 v[58:61], v[190:193], v[198:201], v[58:61]
	v_mfma_f32_16x16x32_bf16 v[46:49], v[138:141], v[206:209], v[46:49]
	v_mfma_f32_16x16x32_bf16 v[42:45], v[190:193], v[206:209], v[42:45]
	v_mfma_f32_16x16x32_bf16 v[30:33], v[138:141], v[214:217], v[30:33]
	v_mfma_f32_16x16x32_bf16 v[26:29], v[190:193], v[214:217], v[26:29]
	v_mfma_f32_16x16x32_bf16 v[14:17], v[138:141], v[222:225], v[14:17]
	v_mfma_f32_16x16x32_bf16 v[10:13], v[190:193], v[222:225], v[10:13]
	v_mfma_f32_16x16x32_bf16 v[62:65], v[186:189], v[202:205], v[62:65]
	v_mfma_f32_16x16x32_bf16 v[58:61], v[194:197], v[202:205], v[58:61]
	v_mfma_f32_16x16x32_bf16 v[46:49], v[186:189], v[210:213], v[46:49]
	v_mfma_f32_16x16x32_bf16 v[42:45], v[194:197], v[210:213], v[42:45]
	v_mfma_f32_16x16x32_bf16 v[30:33], v[186:189], v[218:221], v[30:33]
	v_mfma_f32_16x16x32_bf16 v[26:29], v[194:197], v[218:221], v[26:29]
	v_mfma_f32_16x16x32_bf16 v[14:17], v[186:189], v[226:229], v[14:17]
	v_mfma_f32_16x16x32_bf16 v[10:13], v[194:197], v[226:229], v[10:13]
	s_setprio 0
	s_barrier
	s_add_u32 s58, s58, 0x40080
	s_addc_u32 s59, s59, 0
	s_add_i32 s60, s60, s64
	v_lshl_add_u64 v[138:139], s[58:59], 0, v[152:153]
	s_mov_b32 m0, s60
	s_nop 0
	global_load_lds_dwordx4 v[138:139], off
	v_lshl_add_u64 v[138:139], s[58:59], 0, v[156:157]
	s_add_i32 m0, s60, 0x2000
	s_nop 0
	global_load_lds_dwordx4 v[138:139], off
	s_waitcnt vmcnt(6)
	s_barrier
	s_setprio 1
	v_mfma_f32_16x16x32_bf16 v[54:57], v[230:233], v[198:201], v[54:57]
	v_mfma_f32_16x16x32_bf16 v[50:53], v[238:241], v[198:201], v[50:53]
	v_mfma_f32_16x16x32_bf16 v[38:41], v[230:233], v[206:209], v[38:41]
	v_mfma_f32_16x16x32_bf16 v[34:37], v[238:241], v[206:209], v[34:37]
	v_mfma_f32_16x16x32_bf16 v[22:25], v[230:233], v[214:217], v[22:25]
	v_mfma_f32_16x16x32_bf16 v[18:21], v[238:241], v[214:217], v[18:21]
	v_mfma_f32_16x16x32_bf16 v[6:9], v[230:233], v[222:225], v[6:9]
	v_mfma_f32_16x16x32_bf16 v[2:5], v[238:241], v[222:225], v[2:5]
	v_mfma_f32_16x16x32_bf16 v[54:57], v[234:237], v[202:205], v[54:57]
	v_mfma_f32_16x16x32_bf16 v[50:53], v[242:245], v[202:205], v[50:53]
	v_mfma_f32_16x16x32_bf16 v[38:41], v[234:237], v[210:213], v[38:41]
	v_mfma_f32_16x16x32_bf16 v[34:37], v[242:245], v[210:213], v[34:37]
	v_mfma_f32_16x16x32_bf16 v[22:25], v[234:237], v[218:221], v[22:25]
	v_mfma_f32_16x16x32_bf16 v[18:21], v[242:245], v[218:221], v[18:21]
	v_mfma_f32_16x16x32_bf16 v[6:9], v[234:237], v[226:229], v[6:9]
	v_mfma_f32_16x16x32_bf16 v[2:5], v[242:245], v[226:229], v[2:5]
	s_setprio 0
	s_add_i32 s47, s47, 2
	s_add_u32 s56, s56, 0x100
	s_addc_u32 s57, s57, 0
	s_add_u32 s43, s43, 0x100
	s_addc_u32 s46, s46, 0
	s_cmp_gt_u32 s47, 13
	s_barrier
	s_cbranch_scc0 .LBB0_762
	v_lshl_add_u32 v142, s50, 8, v144
	v_lshl_or_b32 v140, s20, 8, v146
	v_ashrrev_i32_e32 v143, 31, v142
	v_ashrrev_i32_e32 v141, 31, v140
	v_lshlrev_b64 v[138:139], 10, v[142:143]
	v_lshl_add_u64 v[138:139], v[138:139], 0, v[140:141]
	v_lshlrev_b64 v[138:139], 1, v[138:139]
	v_readlane_b32 s74, v254, 46
	s_and_b64 vcc, exec, s[2:3]
	s_mov_b32 s20, s40
	s_mov_b32 s50, s42
	s_mov_b64 s[58:59], s[48:49]
	s_mov_b64 s[56:57], s[44:45]
	v_readlane_b32 s75, v254, 47
	v_mov_b32_e32 v203, v138
	v_add_u32_e32 v204, 0x8000, v138
	v_add_u32_e32 v205, 0x10000, v138
	v_add_u32_e32 v206, 0x18000, v138
	v_add_u32_e32 v207, 0x40000, v138
	v_add_u32_e32 v208, 0x48000, v138
	v_add_u32_e32 v209, 0x50000, v138
	v_add_u32_e32 v210, 0x58000, v138
	global_load_dwordx4 v[212:215], v203, s[18:19]
	global_load_dwordx4 v[216:219], v203, s[0:1]
	global_load_dwordx4 v[220:223], v203, s[18:19] offset:256
	global_load_dwordx4 v[224:227], v203, s[0:1] offset:256
	global_load_dwordx4 v[228:231], v204, s[18:19]
	global_load_dwordx4 v[232:235], v204, s[0:1]
	global_load_dwordx4 v[236:239], v204, s[18:19] offset:256
	global_load_dwordx4 v[240:243], v204, s[0:1] offset:256
	global_load_dwordx4 v[244:247], v205, s[18:19]
	global_load_dwordx4 v[248:251], v205, s[0:1]
	s_waitcnt vmcnt(8)
	v_lshlrev_b32_e32 v143, 16, v212
	v_lshlrev_b32_e32 v169, 16, v216
	v_and_b32_e32 v185, 0xffff0000, v212
	v_and_b32_e32 v212, 0xffff0000, v216
	v_lshlrev_b32_e32 v216, 16, v213
	v_lshlrev_b32_e32 v198, 16, v217
	v_and_b32_e32 v213, 0xffff0000, v213
	v_and_b32_e32 v217, 0xffff0000, v217
	v_lshlrev_b32_e32 v199, 16, v214
	v_lshlrev_b32_e32 v200, 16, v218
	v_and_b32_e32 v214, 0xffff0000, v214
	v_and_b32_e32 v218, 0xffff0000, v218
	v_lshlrev_b32_e32 v201, 16, v215
	v_lshlrev_b32_e32 v202, 16, v219
	v_and_b32_e32 v215, 0xffff0000, v215
	v_and_b32_e32 v219, 0xffff0000, v219
	v_fmac_f32_e32 v213, v129, v217
	v_fmac_f32_e32 v214, v123, v218
	v_fmac_f32_e32 v215, v125, v219
	v_fmac_f32_e32 v143, v126, v169
	v_fmac_f32_e32 v185, v127, v212
	v_fmac_f32_e32 v216, v128, v198
	v_fmac_f32_e32 v199, v122, v200
	v_fmac_f32_e32 v201, v124, v202
	v_cvt_pk_bf16_f32 v122, v143, v185
	v_cvt_pk_bf16_f32 v123, v216, v213
	v_cvt_pk_bf16_f32 v124, v199, v214
	v_cvt_pk_bf16_f32 v125, v201, v215
	global_store_dwordx4 v203, v[122:125], s[26:27]
	global_load_dwordx4 v[212:215], v205, s[18:19] offset:256
	global_load_dwordx4 v[216:219], v205, s[0:1] offset:256
	s_waitcnt vmcnt(9)
	v_lshlrev_b32_e32 v122, 16, v220
	v_lshlrev_b32_e32 v123, 16, v224
	v_and_b32_e32 v124, 0xffff0000, v220
	v_and_b32_e32 v125, 0xffff0000, v224
	v_lshlrev_b32_e32 v220, 16, v221
	v_lshlrev_b32_e32 v143, 16, v225
	v_and_b32_e32 v221, 0xffff0000, v221
	v_and_b32_e32 v169, 0xffff0000, v225
	v_lshlrev_b32_e32 v185, 16, v222
	v_lshlrev_b32_e32 v224, 16, v226
	v_and_b32_e32 v222, 0xffff0000, v222
	v_and_b32_e32 v225, 0xffff0000, v226
	v_lshlrev_b32_e32 v226, 16, v223
	v_lshlrev_b32_e32 v198, 16, v227
	v_and_b32_e32 v223, 0xffff0000, v223
	v_and_b32_e32 v227, 0xffff0000, v227
	v_fmac_f32_e32 v122, v118, v123
	v_fmac_f32_e32 v124, v119, v125
	v_fmac_f32_e32 v220, v120, v143
	v_fmac_f32_e32 v221, v121, v169
	v_fmac_f32_e32 v185, v114, v224
	v_fmac_f32_e32 v222, v115, v225
	v_fmac_f32_e32 v226, v116, v198
	v_fmac_f32_e32 v223, v117, v227
	v_cvt_pk_bf16_f32 v114, v122, v124
	v_cvt_pk_bf16_f32 v115, v220, v221
	v_cvt_pk_bf16_f32 v116, v185, v222
	v_cvt_pk_bf16_f32 v117, v226, v223
	global_store_dwordx4 v203, v[114:117], s[26:27] offset:256
	global_load_dwordx4 v[220:223], v206, s[18:19]
	global_load_dwordx4 v[224:227], v206, s[0:1]
	s_waitcnt vmcnt(10)
	v_lshlrev_b32_e32 v122, 16, v228
	v_lshlrev_b32_e32 v123, 16, v232
	v_and_b32_e32 v228, 0xffff0000, v228
	v_and_b32_e32 v232, 0xffff0000, v232
	v_lshlrev_b32_e32 v124, 16, v229
	v_lshlrev_b32_e32 v125, 16, v233
	v_and_b32_e32 v229, 0xffff0000, v229
	v_and_b32_e32 v233, 0xffff0000, v233
	v_lshlrev_b32_e32 v126, 16, v230
	v_lshlrev_b32_e32 v127, 16, v234
	v_and_b32_e32 v230, 0xffff0000, v230
	v_and_b32_e32 v234, 0xffff0000, v234
	v_lshlrev_b32_e32 v128, 16, v231
	v_lshlrev_b32_e32 v129, 16, v235
	v_and_b32_e32 v231, 0xffff0000, v231
	v_and_b32_e32 v235, 0xffff0000, v235
	v_fmac_f32_e32 v228, v111, v232
	v_fmac_f32_e32 v229, v113, v233
	v_fmac_f32_e32 v230, v107, v234
	v_fmac_f32_e32 v231, v109, v235
	v_fmac_f32_e32 v122, v110, v123
	v_fmac_f32_e32 v124, v112, v125
	v_fmac_f32_e32 v126, v106, v127
	v_fmac_f32_e32 v128, v108, v129
	v_cvt_pk_bf16_f32 v106, v122, v228
	v_cvt_pk_bf16_f32 v107, v124, v229
	v_cvt_pk_bf16_f32 v108, v126, v230
	v_cvt_pk_bf16_f32 v109, v128, v231
	global_store_dwordx4 v204, v[106:109], s[26:27]
	global_load_dwordx4 v[228:231], v206, s[18:19] offset:256
	global_load_dwordx4 v[232:235], v206, s[0:1] offset:256
	s_waitcnt vmcnt(11)
	v_lshlrev_b32_e32 v106, 16, v236
	v_lshlrev_b32_e32 v107, 16, v240
	v_and_b32_e32 v108, 0xffff0000, v236
	v_and_b32_e32 v109, 0xffff0000, v240
	v_lshlrev_b32_e32 v236, 16, v237
	v_lshlrev_b32_e32 v240, 16, v241
	v_and_b32_e32 v237, 0xffff0000, v237
	v_and_b32_e32 v241, 0xffff0000, v241
	v_lshlrev_b32_e32 v126, 16, v238
	v_lshlrev_b32_e32 v127, 16, v242
	v_and_b32_e32 v238, 0xffff0000, v238
	v_and_b32_e32 v242, 0xffff0000, v242
	v_lshlrev_b32_e32 v128, 16, v239
	v_lshlrev_b32_e32 v129, 16, v243
	v_and_b32_e32 v239, 0xffff0000, v239
	v_and_b32_e32 v243, 0xffff0000, v243
	v_fmac_f32_e32 v106, v102, v107
	v_fmac_f32_e32 v108, v103, v109
	v_fmac_f32_e32 v236, v104, v240
	v_fmac_f32_e32 v237, v105, v241
	v_fmac_f32_e32 v126, v98, v127
	v_fmac_f32_e32 v238, v99, v242
	v_fmac_f32_e32 v128, v100, v129
	v_fmac_f32_e32 v239, v101, v243
	v_cvt_pk_bf16_f32 v98, v106, v108
	v_cvt_pk_bf16_f32 v99, v236, v237
	v_cvt_pk_bf16_f32 v100, v126, v238
	v_cvt_pk_bf16_f32 v101, v128, v239
	global_store_dwordx4 v204, v[98:101], s[26:27] offset:256
	global_load_dwordx4 v[236:239], v207, s[18:19]
	global_load_dwordx4 v[240:243], v207, s[0:1]
	s_waitcnt vmcnt(12)
	v_lshlrev_b32_e32 v106, 16, v244
	v_lshlrev_b32_e32 v107, 16, v248
	v_and_b32_e32 v244, 0xffff0000, v244
	v_and_b32_e32 v248, 0xffff0000, v248
	v_lshlrev_b32_e32 v108, 16, v245
	v_lshlrev_b32_e32 v109, 16, v249
	v_and_b32_e32 v245, 0xffff0000, v245
	v_and_b32_e32 v249, 0xffff0000, v249
	v_lshlrev_b32_e32 v110, 16, v246
	v_lshlrev_b32_e32 v111, 16, v250
	v_and_b32_e32 v246, 0xffff0000, v246
	v_and_b32_e32 v250, 0xffff0000, v250
	v_lshlrev_b32_e32 v112, 16, v247
	v_lshlrev_b32_e32 v113, 16, v251
	v_and_b32_e32 v247, 0xffff0000, v247
	v_and_b32_e32 v251, 0xffff0000, v251
	v_fmac_f32_e32 v244, v95, v248
	v_fmac_f32_e32 v245, v97, v249
	v_fmac_f32_e32 v246, v91, v250
	v_fmac_f32_e32 v247, v93, v251
	v_fmac_f32_e32 v106, v94, v107
	v_fmac_f32_e32 v108, v96, v109
	v_fmac_f32_e32 v110, v90, v111
	v_fmac_f32_e32 v112, v92, v113
	v_cvt_pk_bf16_f32 v90, v106, v244
	v_cvt_pk_bf16_f32 v91, v108, v245
	v_cvt_pk_bf16_f32 v92, v110, v246
	v_cvt_pk_bf16_f32 v93, v112, v247
	global_store_dwordx4 v205, v[90:93], s[26:27]
	global_load_dwordx4 v[244:247], v207, s[18:19] offset:256
	global_load_dwordx4 v[248:251], v207, s[0:1] offset:256
	s_waitcnt vmcnt(12)
	v_lshlrev_b32_e32 v90, 16, v212
	v_lshlrev_b32_e32 v91, 16, v216
	v_and_b32_e32 v92, 0xffff0000, v212
	v_and_b32_e32 v93, 0xffff0000, v216
	v_lshlrev_b32_e32 v212, 16, v213
	v_lshlrev_b32_e32 v216, 16, v217
	v_and_b32_e32 v213, 0xffff0000, v213
	v_and_b32_e32 v217, 0xffff0000, v217
	v_lshlrev_b32_e32 v110, 16, v214
	v_lshlrev_b32_e32 v111, 16, v218
	v_and_b32_e32 v214, 0xffff0000, v214
	v_and_b32_e32 v218, 0xffff0000, v218
	v_lshlrev_b32_e32 v112, 16, v215
	v_lshlrev_b32_e32 v113, 16, v219
	v_and_b32_e32 v215, 0xffff0000, v215
	v_and_b32_e32 v219, 0xffff0000, v219
	v_fmac_f32_e32 v90, v86, v91
	v_fmac_f32_e32 v92, v87, v93
	v_fmac_f32_e32 v212, v88, v216
	v_fmac_f32_e32 v213, v89, v217
	v_fmac_f32_e32 v110, v82, v111
	v_fmac_f32_e32 v214, v83, v218
	v_fmac_f32_e32 v112, v84, v113
	v_fmac_f32_e32 v215, v85, v219
	v_cvt_pk_bf16_f32 v82, v90, v92
	v_cvt_pk_bf16_f32 v83, v212, v213
	v_cvt_pk_bf16_f32 v84, v110, v214
	v_cvt_pk_bf16_f32 v85, v112, v215
	global_store_dwordx4 v205, v[82:85], s[26:27] offset:256
	global_load_dwordx4 v[212:215], v208, s[18:19]
	global_load_dwordx4 v[216:219], v208, s[0:1]
	s_waitcnt vmcnt(12)
	v_lshlrev_b32_e32 v90, 16, v220
	v_lshlrev_b32_e32 v91, 16, v224
	v_and_b32_e32 v220, 0xffff0000, v220
	v_and_b32_e32 v224, 0xffff0000, v224
	v_lshlrev_b32_e32 v92, 16, v221
	v_lshlrev_b32_e32 v93, 16, v225
	v_and_b32_e32 v221, 0xffff0000, v221
	v_and_b32_e32 v225, 0xffff0000, v225
	v_lshlrev_b32_e32 v94, 16, v222
	v_lshlrev_b32_e32 v95, 16, v226
	v_and_b32_e32 v222, 0xffff0000, v222
	v_and_b32_e32 v226, 0xffff0000, v226
	v_lshlrev_b32_e32 v96, 16, v223
	v_lshlrev_b32_e32 v97, 16, v227
	v_and_b32_e32 v223, 0xffff0000, v223
	v_and_b32_e32 v227, 0xffff0000, v227
	v_fmac_f32_e32 v220, v79, v224
	v_fmac_f32_e32 v221, v81, v225
	v_fmac_f32_e32 v222, v75, v226
	v_fmac_f32_e32 v223, v77, v227
	v_fmac_f32_e32 v90, v78, v91
	v_fmac_f32_e32 v92, v80, v93
	v_fmac_f32_e32 v94, v74, v95
	v_fmac_f32_e32 v96, v76, v97
	v_cvt_pk_bf16_f32 v74, v90, v220
	v_cvt_pk_bf16_f32 v75, v92, v221
	v_cvt_pk_bf16_f32 v76, v94, v222
	v_cvt_pk_bf16_f32 v77, v96, v223
	global_store_dwordx4 v206, v[74:77], s[26:27]
	global_load_dwordx4 v[220:223], v208, s[18:19] offset:256
	global_load_dwordx4 v[224:227], v208, s[0:1] offset:256
	s_waitcnt vmcnt(12)
	v_lshlrev_b32_e32 v74, 16, v228
	v_lshlrev_b32_e32 v75, 16, v232
	v_and_b32_e32 v76, 0xffff0000, v228
	v_and_b32_e32 v77, 0xffff0000, v232
	v_lshlrev_b32_e32 v228, 16, v229
	v_lshlrev_b32_e32 v232, 16, v233
	v_and_b32_e32 v229, 0xffff0000, v229
	v_and_b32_e32 v233, 0xffff0000, v233
	v_lshlrev_b32_e32 v94, 16, v230
	v_lshlrev_b32_e32 v95, 16, v234
	v_and_b32_e32 v230, 0xffff0000, v230
	v_and_b32_e32 v234, 0xffff0000, v234
	v_lshlrev_b32_e32 v96, 16, v231
	v_lshlrev_b32_e32 v97, 16, v235
	v_and_b32_e32 v231, 0xffff0000, v231
	v_and_b32_e32 v235, 0xffff0000, v235
	v_fmac_f32_e32 v74, v70, v75
	v_fmac_f32_e32 v76, v71, v77
	v_fmac_f32_e32 v228, v72, v232
	v_fmac_f32_e32 v229, v73, v233
	v_fmac_f32_e32 v94, v66, v95
	v_fmac_f32_e32 v230, v67, v234
	v_fmac_f32_e32 v96, v68, v97
	v_fmac_f32_e32 v231, v69, v235
	v_cvt_pk_bf16_f32 v66, v74, v76
	v_cvt_pk_bf16_f32 v67, v228, v229
	v_cvt_pk_bf16_f32 v68, v94, v230
	v_cvt_pk_bf16_f32 v69, v96, v231
	global_store_dwordx4 v206, v[66:69], s[26:27] offset:256
	global_load_dwordx4 v[228:231], v209, s[18:19]
	global_load_dwordx4 v[232:235], v209, s[0:1]
	s_waitcnt vmcnt(12)
	v_lshlrev_b32_e32 v74, 16, v236
	v_lshlrev_b32_e32 v75, 16, v240
	v_and_b32_e32 v236, 0xffff0000, v236
	v_and_b32_e32 v240, 0xffff0000, v240
	v_lshlrev_b32_e32 v76, 16, v237
	v_lshlrev_b32_e32 v77, 16, v241
	v_and_b32_e32 v237, 0xffff0000, v237
	v_and_b32_e32 v241, 0xffff0000, v241
	v_lshlrev_b32_e32 v78, 16, v238
	v_lshlrev_b32_e32 v79, 16, v242
	v_and_b32_e32 v238, 0xffff0000, v238
	v_and_b32_e32 v242, 0xffff0000, v242
	v_lshlrev_b32_e32 v80, 16, v239
	v_lshlrev_b32_e32 v81, 16, v243
	v_and_b32_e32 v239, 0xffff0000, v239
	v_and_b32_e32 v243, 0xffff0000, v243
	v_fmac_f32_e32 v236, v63, v240
	v_fmac_f32_e32 v237, v65, v241
	v_fmac_f32_e32 v238, v59, v242
	v_fmac_f32_e32 v239, v61, v243
	v_fmac_f32_e32 v74, v62, v75
	v_fmac_f32_e32 v76, v64, v77
	v_fmac_f32_e32 v78, v58, v79
	v_fmac_f32_e32 v80, v60, v81
	v_cvt_pk_bf16_f32 v58, v74, v236
	v_cvt_pk_bf16_f32 v59, v76, v237
	v_cvt_pk_bf16_f32 v60, v78, v238
	v_cvt_pk_bf16_f32 v61, v80, v239
	global_store_dwordx4 v207, v[58:61], s[26:27]
	global_load_dwordx4 v[236:239], v209, s[18:19] offset:256
	global_load_dwordx4 v[240:243], v209, s[0:1] offset:256
	s_waitcnt vmcnt(12)
	v_lshlrev_b32_e32 v58, 16, v244
	v_lshlrev_b32_e32 v59, 16, v248
	v_and_b32_e32 v60, 0xffff0000, v244
	v_and_b32_e32 v61, 0xffff0000, v248
	v_lshlrev_b32_e32 v244, 16, v245
	v_lshlrev_b32_e32 v248, 16, v249
	v_and_b32_e32 v245, 0xffff0000, v245
	v_and_b32_e32 v249, 0xffff0000, v249
	v_lshlrev_b32_e32 v78, 16, v246
	v_lshlrev_b32_e32 v79, 16, v250
	v_and_b32_e32 v246, 0xffff0000, v246
	v_and_b32_e32 v250, 0xffff0000, v250
	v_lshlrev_b32_e32 v80, 16, v247
	v_lshlrev_b32_e32 v81, 16, v251
	v_and_b32_e32 v247, 0xffff0000, v247
	v_and_b32_e32 v251, 0xffff0000, v251
	v_fmac_f32_e32 v58, v54, v59
	v_fmac_f32_e32 v60, v55, v61
	v_fmac_f32_e32 v244, v56, v248
	v_fmac_f32_e32 v245, v57, v249
	v_fmac_f32_e32 v78, v50, v79
	v_fmac_f32_e32 v246, v51, v250
	v_fmac_f32_e32 v80, v52, v81
	v_fmac_f32_e32 v247, v53, v251
	v_cvt_pk_bf16_f32 v50, v58, v60
	v_cvt_pk_bf16_f32 v51, v244, v245
	v_cvt_pk_bf16_f32 v52, v78, v246
	v_cvt_pk_bf16_f32 v53, v80, v247
	global_store_dwordx4 v207, v[50:53], s[26:27] offset:256
	global_load_dwordx4 v[244:247], v210, s[18:19]
	global_load_dwordx4 v[248:251], v210, s[0:1]
	s_waitcnt vmcnt(12)
	v_lshlrev_b32_e32 v58, 16, v212
	v_lshlrev_b32_e32 v59, 16, v216
	v_and_b32_e32 v212, 0xffff0000, v212
	v_and_b32_e32 v216, 0xffff0000, v216
	v_lshlrev_b32_e32 v60, 16, v213
	v_lshlrev_b32_e32 v61, 16, v217
	v_and_b32_e32 v213, 0xffff0000, v213
	v_and_b32_e32 v217, 0xffff0000, v217
	v_lshlrev_b32_e32 v62, 16, v214
	v_lshlrev_b32_e32 v63, 16, v218
	v_and_b32_e32 v214, 0xffff0000, v214
	v_and_b32_e32 v218, 0xffff0000, v218
	v_lshlrev_b32_e32 v64, 16, v215
	v_lshlrev_b32_e32 v65, 16, v219
	v_and_b32_e32 v215, 0xffff0000, v215
	v_and_b32_e32 v219, 0xffff0000, v219
	v_fmac_f32_e32 v212, v47, v216
	v_fmac_f32_e32 v213, v49, v217
	v_fmac_f32_e32 v214, v43, v218
	v_fmac_f32_e32 v215, v45, v219
	v_fmac_f32_e32 v58, v46, v59
	v_fmac_f32_e32 v60, v48, v61
	v_fmac_f32_e32 v62, v42, v63
	v_fmac_f32_e32 v64, v44, v65
	v_cvt_pk_bf16_f32 v42, v58, v212
	v_cvt_pk_bf16_f32 v43, v60, v213
	v_cvt_pk_bf16_f32 v44, v62, v214
	v_cvt_pk_bf16_f32 v45, v64, v215
	global_store_dwordx4 v208, v[42:45], s[26:27]
	global_load_dwordx4 v[212:215], v210, s[18:19] offset:256
	global_load_dwordx4 v[216:219], v210, s[0:1] offset:256
	s_waitcnt vmcnt(12)
	v_lshlrev_b32_e32 v42, 16, v220
	v_lshlrev_b32_e32 v43, 16, v224
	v_and_b32_e32 v44, 0xffff0000, v220
	v_and_b32_e32 v45, 0xffff0000, v224
	v_lshlrev_b32_e32 v220, 16, v221
	v_lshlrev_b32_e32 v224, 16, v225
	v_and_b32_e32 v221, 0xffff0000, v221
	v_and_b32_e32 v225, 0xffff0000, v225
	v_lshlrev_b32_e32 v62, 16, v222
	v_lshlrev_b32_e32 v63, 16, v226
	v_and_b32_e32 v222, 0xffff0000, v222
	v_and_b32_e32 v226, 0xffff0000, v226
	v_lshlrev_b32_e32 v64, 16, v223
	v_lshlrev_b32_e32 v65, 16, v227
	v_and_b32_e32 v223, 0xffff0000, v223
	v_and_b32_e32 v227, 0xffff0000, v227
	v_fmac_f32_e32 v42, v38, v43
	v_fmac_f32_e32 v44, v39, v45
	v_fmac_f32_e32 v220, v40, v224
	v_fmac_f32_e32 v221, v41, v225
	v_fmac_f32_e32 v62, v34, v63
	v_fmac_f32_e32 v222, v35, v226
	v_fmac_f32_e32 v64, v36, v65
	v_fmac_f32_e32 v223, v37, v227
	v_cvt_pk_bf16_f32 v34, v42, v44
	v_cvt_pk_bf16_f32 v35, v220, v221
	v_cvt_pk_bf16_f32 v36, v62, v222
	v_cvt_pk_bf16_f32 v37, v64, v223
	global_store_dwordx4 v208, v[34:37], s[26:27] offset:256
	s_waitcnt vmcnt(10)
	v_lshlrev_b32_e32 v42, 16, v228
	v_lshlrev_b32_e32 v43, 16, v232
	v_and_b32_e32 v228, 0xffff0000, v228
	v_and_b32_e32 v232, 0xffff0000, v232
	v_lshlrev_b32_e32 v44, 16, v229
	v_lshlrev_b32_e32 v45, 16, v233
	v_and_b32_e32 v229, 0xffff0000, v229
	v_and_b32_e32 v233, 0xffff0000, v233
	v_lshlrev_b32_e32 v46, 16, v230
	v_lshlrev_b32_e32 v47, 16, v234
	v_and_b32_e32 v230, 0xffff0000, v230
	v_and_b32_e32 v234, 0xffff0000, v234
	v_lshlrev_b32_e32 v48, 16, v231
	v_lshlrev_b32_e32 v49, 16, v235
	v_and_b32_e32 v231, 0xffff0000, v231
	v_and_b32_e32 v235, 0xffff0000, v235
	v_fmac_f32_e32 v228, v31, v232
	v_fmac_f32_e32 v229, v33, v233
	v_fmac_f32_e32 v230, v27, v234
	v_fmac_f32_e32 v231, v29, v235
	v_fmac_f32_e32 v42, v30, v43
	v_fmac_f32_e32 v44, v32, v45
	v_fmac_f32_e32 v46, v26, v47
	v_fmac_f32_e32 v48, v28, v49
	v_cvt_pk_bf16_f32 v26, v42, v228
	v_cvt_pk_bf16_f32 v27, v44, v229
	v_cvt_pk_bf16_f32 v28, v46, v230
	v_cvt_pk_bf16_f32 v29, v48, v231
	global_store_dwordx4 v209, v[26:29], s[26:27]
	s_waitcnt vmcnt(8)
	v_lshlrev_b32_e32 v26, 16, v236
	v_lshlrev_b32_e32 v27, 16, v240
	v_and_b32_e32 v28, 0xffff0000, v236
	v_and_b32_e32 v29, 0xffff0000, v240
	v_lshlrev_b32_e32 v236, 16, v237
	v_lshlrev_b32_e32 v240, 16, v241
	v_and_b32_e32 v237, 0xffff0000, v237
	v_and_b32_e32 v241, 0xffff0000, v241
	v_lshlrev_b32_e32 v46, 16, v238
	v_lshlrev_b32_e32 v47, 16, v242
	v_and_b32_e32 v238, 0xffff0000, v238
	v_and_b32_e32 v242, 0xffff0000, v242
	v_lshlrev_b32_e32 v48, 16, v239
	v_lshlrev_b32_e32 v49, 16, v243
	v_and_b32_e32 v239, 0xffff0000, v239
	v_and_b32_e32 v243, 0xffff0000, v243
	v_fmac_f32_e32 v26, v22, v27
	v_fmac_f32_e32 v28, v23, v29
	v_fmac_f32_e32 v236, v24, v240
	v_fmac_f32_e32 v237, v25, v241
	v_fmac_f32_e32 v46, v18, v47
	v_fmac_f32_e32 v238, v19, v242
	v_fmac_f32_e32 v48, v20, v49
	v_fmac_f32_e32 v239, v21, v243
	v_cvt_pk_bf16_f32 v18, v26, v28
	v_cvt_pk_bf16_f32 v19, v236, v237
	v_cvt_pk_bf16_f32 v20, v46, v238
	v_cvt_pk_bf16_f32 v21, v48, v239
	global_store_dwordx4 v209, v[18:21], s[26:27] offset:256
	s_waitcnt vmcnt(6)
	v_lshlrev_b32_e32 v26, 16, v244
	v_lshlrev_b32_e32 v27, 16, v248
	v_and_b32_e32 v244, 0xffff0000, v244
	v_and_b32_e32 v248, 0xffff0000, v248
	v_lshlrev_b32_e32 v28, 16, v245
	v_lshlrev_b32_e32 v29, 16, v249
	v_and_b32_e32 v245, 0xffff0000, v245
	v_and_b32_e32 v249, 0xffff0000, v249
	v_lshlrev_b32_e32 v30, 16, v246
	v_lshlrev_b32_e32 v31, 16, v250
	v_and_b32_e32 v246, 0xffff0000, v246
	v_and_b32_e32 v250, 0xffff0000, v250
	v_lshlrev_b32_e32 v32, 16, v247
	v_lshlrev_b32_e32 v33, 16, v251
	v_and_b32_e32 v247, 0xffff0000, v247
	v_and_b32_e32 v251, 0xffff0000, v251
	v_fmac_f32_e32 v244, v15, v248
	v_fmac_f32_e32 v245, v17, v249
	v_fmac_f32_e32 v246, v11, v250
	v_fmac_f32_e32 v247, v13, v251
	v_fmac_f32_e32 v26, v14, v27
	v_fmac_f32_e32 v28, v16, v29
	v_fmac_f32_e32 v30, v10, v31
	v_fmac_f32_e32 v32, v12, v33
	v_cvt_pk_bf16_f32 v10, v26, v244
	v_cvt_pk_bf16_f32 v11, v28, v245
	v_cvt_pk_bf16_f32 v12, v30, v246
	v_cvt_pk_bf16_f32 v13, v32, v247
	global_store_dwordx4 v210, v[10:13], s[26:27]
	s_waitcnt vmcnt(4)
	v_lshlrev_b32_e32 v24, 16, v214
	v_lshlrev_b32_e32 v10, 16, v212
	v_lshlrev_b32_e32 v11, 16, v216
	v_and_b32_e32 v12, 0xffff0000, v212
	v_and_b32_e32 v13, 0xffff0000, v216
	v_lshlrev_b32_e32 v212, 16, v213
	v_lshlrev_b32_e32 v216, 16, v217
	v_and_b32_e32 v213, 0xffff0000, v213
	v_and_b32_e32 v217, 0xffff0000, v217
	v_lshlrev_b32_e32 v25, 16, v218
	v_and_b32_e32 v214, 0xffff0000, v214
	v_and_b32_e32 v218, 0xffff0000, v218
	v_lshlrev_b32_e32 v26, 16, v215
	v_lshlrev_b32_e32 v27, 16, v219
	v_and_b32_e32 v215, 0xffff0000, v215
	v_and_b32_e32 v219, 0xffff0000, v219
	v_fmac_f32_e32 v10, v6, v11
	v_fmac_f32_e32 v12, v7, v13
	v_fmac_f32_e32 v212, v8, v216
	v_fmac_f32_e32 v213, v9, v217
	v_fmac_f32_e32 v24, v2, v25
	v_fmac_f32_e32 v214, v3, v218
	v_fmac_f32_e32 v26, v4, v27
	v_fmac_f32_e32 v215, v5, v219
	v_cvt_pk_bf16_f32 v2, v10, v12
	v_cvt_pk_bf16_f32 v3, v212, v213
	v_cvt_pk_bf16_f32 v4, v24, v214
	v_cvt_pk_bf16_f32 v5, v26, v215
	global_store_dwordx4 v210, v[2:5], s[26:27] offset:256
	s_cbranch_vccz .LBB0_755
	s_waitcnt vmcnt(0)
	s_cmpk_gt_u32 s24, 0xff
	s_cbranch_scc1 .LBB0_766
	s_barrier

.LBB0_870:
	s_lshl_b32 s24, s34, 8
	s_add_i32 s1, s24, s63
	s_lshl_b32 s0, s22, 5
	v_or_b32_e32 v132, s1, v1
	s_lshl_b32 s1, s36, 8
	s_or_b32 s0, s1, s0
	v_or_b32_e32 v130, s0, v149
	v_ashrrev_i32_e32 v133, 31, v132
	v_ashrrev_i32_e32 v131, 31, v130
	v_lshlrev_b64 v[134:135], 10, v[132:133]
	v_lshl_add_u64 v[142:143], v[134:135], 0, v[130:131]
	v_lshl_add_u64 v[144:145], v[142:143], 2, s[52:53]
	s_barrier
	v_lshlrev_b32_e32 v236, 2, v142
	v_lshlrev_b32_e32 v237, 2, v142
	v_add_u32_e32 v237, 0x10000, v237
	v_lshlrev_b32_e32 v238, 2, v142
	v_add_u32_e32 v238, 0x20000, v238
	v_lshlrev_b32_e32 v239, 2, v142
	v_add_u32_e32 v239, 0x30000, v239
	v_lshlrev_b32_e32 v240, 2, v142
	v_add_u32_e32 v240, 0x80000, v240
	v_lshlrev_b32_e32 v241, 2, v142
	v_add_u32_e32 v241, 0x90000, v241
	v_lshlrev_b32_e32 v242, 2, v142
	v_add_u32_e32 v242, 0xa0000, v242
	v_lshlrev_b32_e32 v243, 2, v142
	v_add_u32_e32 v243, 0xb0000, v243
	global_load_dwordx4 v[188:191], v236, s[52:53]
	global_load_dwordx4 v[192:195], v236, s[52:53] offset:16
	global_load_dwordx4 v[196:199], v236, s[52:53] offset:512
	global_load_dwordx4 v[200:203], v236, s[52:53] offset:528
	global_load_dwordx4 v[204:207], v237, s[52:53]
	global_load_dwordx4 v[208:211], v237, s[52:53] offset:16
	global_load_dwordx4 v[212:215], v237, s[52:53] offset:512
	global_load_dwordx4 v[216:219], v237, s[52:53] offset:528
	global_load_dwordx4 v[220:223], v238, s[52:53]
	global_load_dwordx4 v[224:227], v238, s[52:53] offset:16
	global_load_dwordx4 v[228:231], v238, s[52:53] offset:512
	global_load_dwordx4 v[232:235], v238, s[52:53] offset:528
	v_lshl_add_u64 v[142:143], v[142:143], 1, s[8:9]
	v_cmp_lt_i32_e64 s[0:1], v163, v161
	s_lshl_b32 s2, s22, 2
	s_add_i32 s2, s2, 0
	v_cmp_gt_u32_e32 vcc, 16, v148
	v_lshl_add_u32 v155, v158, 4, s2
	s_waitcnt vmcnt(11)
	v_pk_add_f32 v[128:129], v[128:129], v[190:191]
	v_pk_add_f32 v[126:127], v[126:127], v[188:189]
	s_waitcnt vmcnt(10)
	v_pk_add_f32 v[124:125], v[124:125], v[194:195]
	v_pk_add_f32 v[122:123], v[122:123], v[192:193]
	v_cvt_pk_bf16_f32 v134, v126, v127
	v_cvt_pk_bf16_f32 v135, v128, v129
	v_mul_f32_e32 v147, v125, v125
	v_cvt_pk_bf16_f32 v136, v122, v123
	v_cvt_pk_bf16_f32 v137, v124, v125
	global_store_dwordx4 v[142:143], v[134:137], off
	global_load_dwordx4 v[188:191], v239, s[52:53]
	global_load_dwordx4 v[192:195], v239, s[52:53] offset:16
	s_nop 0
	v_cndmask_b32_e64 v144, v160, v163, s[0:1]
	v_lshlrev_b32_e32 v153, 2, v144
	v_mul_f32_e32 v144, v127, v127
	v_mul_f32_e32 v145, v129, v129
	v_mul_f32_e32 v146, v123, v123
	v_fmac_f32_e32 v144, v126, v126
	v_fmac_f32_e32 v145, v128, v128
	v_fmac_f32_e32 v146, v122, v122
	v_fmac_f32_e32 v147, v124, v124
	v_add_f32_e32 v144, v144, v145
	v_add_f32_e32 v145, v146, v147
	v_add_f32_e32 v144, v144, v145
	v_cmp_lt_i32_e64 s[0:1], v162, v161
	s_waitcnt vmcnt(12)
	v_pk_add_f32 v[120:121], v[120:121], v[198:199]
	v_pk_add_f32 v[118:119], v[118:119], v[196:197]
	s_waitcnt vmcnt(11)
	v_pk_add_f32 v[116:117], v[116:117], v[202:203]
	v_pk_add_f32 v[114:115], v[114:115], v[200:201]
	v_mul_f32_e32 v134, v119, v119
	v_mul_f32_e32 v135, v121, v121
	v_mul_f32_e32 v136, v115, v115
	v_mul_f32_e32 v137, v117, v117
	v_fmac_f32_e32 v134, v118, v118
	v_fmac_f32_e32 v135, v120, v120
	v_fmac_f32_e32 v136, v114, v114
	v_fmac_f32_e32 v137, v116, v116
	v_add_f32_e32 v134, v134, v135
	v_add_f32_e32 v135, v136, v137
	v_add_f32_e32 v134, v134, v135
	v_add_f32_e32 v134, v144, v134
	ds_bpermute_b32 v135, v153, v134
	v_cndmask_b32_e64 v138, v160, v162, s[0:1]
	v_lshlrev_b32_e32 v157, 2, v138
	v_cvt_pk_bf16_f32 v136, v118, v119
	v_cvt_pk_bf16_f32 v137, v120, v121
	s_waitcnt lgkmcnt(0)
	v_add_f32_e32 v134, v134, v135
	ds_bpermute_b32 v135, v157, v134
	v_cvt_pk_bf16_f32 v138, v114, v115
	v_cvt_pk_bf16_f32 v139, v116, v117
	global_store_dwordx4 v[142:143], v[136:139], off offset:256
	global_load_dwordx4 v[196:199], v239, s[52:53] offset:512
	global_load_dwordx4 v[200:203], v239, s[52:53] offset:528
	s_and_saveexec_b64 s[0:1], vcc
	s_cbranch_execz .LBB0_872
	s_waitcnt lgkmcnt(0)
	v_add_f32_e32 v134, v134, v135
	ds_write_b32 v155, v134
.LBB0_872:
	s_or_b64 exec, exec, s[0:1]
	v_or_b32_e32 v134, 16, v132
	s_waitcnt lgkmcnt(0)
	v_ashrrev_i32_e32 v135, 31, v134
	v_lshlrev_b64 v[134:135], 10, v[134:135]
	v_lshl_add_u64 v[142:143], v[134:135], 0, v[130:131]
	v_lshl_add_u64 v[144:145], v[142:143], 2, s[52:53]
	v_lshl_add_u64 v[142:143], v[142:143], 1, s[8:9]
	s_waitcnt vmcnt(13)
	v_pk_add_f32 v[112:113], v[112:113], v[206:207]
	v_pk_add_f32 v[110:111], v[110:111], v[204:205]
	s_waitcnt vmcnt(12)
	v_pk_add_f32 v[108:109], v[108:109], v[210:211]
	v_pk_add_f32 v[106:107], v[106:107], v[208:209]
	v_cvt_pk_bf16_f32 v134, v110, v111
	v_cvt_pk_bf16_f32 v135, v112, v113
	v_mul_f32_e32 v147, v109, v109
	v_cvt_pk_bf16_f32 v136, v106, v107
	v_cvt_pk_bf16_f32 v137, v108, v109
	global_store_dwordx4 v[142:143], v[134:137], off
	global_load_dwordx4 v[204:207], v240, s[52:53]
	global_load_dwordx4 v[208:211], v240, s[52:53] offset:16
	s_nop 0
	v_mul_f32_e32 v144, v111, v111
	v_mul_f32_e32 v145, v113, v113
	v_mul_f32_e32 v146, v107, v107
	v_fmac_f32_e32 v144, v110, v110
	v_fmac_f32_e32 v145, v112, v112
	v_fmac_f32_e32 v146, v106, v106
	v_fmac_f32_e32 v147, v108, v108
	v_add_f32_e32 v144, v144, v145
	v_add_f32_e32 v145, v146, v147
	v_add_f32_e32 v144, v144, v145
	s_waitcnt vmcnt(14)
	v_pk_add_f32 v[104:105], v[104:105], v[214:215]
	v_pk_add_f32 v[102:103], v[102:103], v[212:213]
	s_waitcnt vmcnt(13)
	v_pk_add_f32 v[100:101], v[100:101], v[218:219]
	v_pk_add_f32 v[98:99], v[98:99], v[216:217]
	v_mul_f32_e32 v134, v103, v103
	v_mul_f32_e32 v135, v105, v105
	v_mul_f32_e32 v136, v99, v99
	v_mul_f32_e32 v137, v101, v101
	v_fmac_f32_e32 v134, v102, v102
	v_fmac_f32_e32 v135, v104, v104
	v_fmac_f32_e32 v136, v98, v98
	v_fmac_f32_e32 v137, v100, v100
	v_add_f32_e32 v134, v134, v135
	v_add_f32_e32 v135, v136, v137
	v_add_f32_e32 v134, v134, v135
	v_add_f32_e32 v134, v144, v134
	ds_bpermute_b32 v135, v153, v134
	v_cvt_pk_bf16_f32 v136, v102, v103
	v_cvt_pk_bf16_f32 v137, v104, v105
	v_cvt_pk_bf16_f32 v138, v98, v99
	v_cvt_pk_bf16_f32 v139, v100, v101
	s_waitcnt lgkmcnt(0)
	v_add_f32_e32 v134, v134, v135
	ds_bpermute_b32 v135, v157, v134
	global_store_dwordx4 v[142:143], v[136:139], off offset:256
	global_load_dwordx4 v[212:215], v240, s[52:53] offset:512
	global_load_dwordx4 v[216:219], v240, s[52:53] offset:528
	s_and_saveexec_b64 s[0:1], vcc
	s_cbranch_execz .LBB0_874
	s_waitcnt lgkmcnt(0)
	v_add_f32_e32 v134, v134, v135
	ds_write_b32 v155, v134 offset:256
.LBB0_874:
	s_or_b64 exec, exec, s[0:1]
	v_or_b32_e32 v134, 32, v132
	s_waitcnt lgkmcnt(0)
	v_ashrrev_i32_e32 v135, 31, v134
	v_lshlrev_b64 v[134:135], 10, v[134:135]
	v_lshl_add_u64 v[142:143], v[134:135], 0, v[130:131]
	v_lshl_add_u64 v[144:145], v[142:143], 2, s[52:53]
	v_lshl_add_u64 v[142:143], v[142:143], 1, s[8:9]
	s_waitcnt vmcnt(15)
	v_pk_add_f32 v[96:97], v[96:97], v[222:223]
	v_pk_add_f32 v[94:95], v[94:95], v[220:221]
	s_waitcnt vmcnt(14)
	v_pk_add_f32 v[92:93], v[92:93], v[226:227]
	v_pk_add_f32 v[90:91], v[90:91], v[224:225]
	v_cvt_pk_bf16_f32 v134, v94, v95
	v_cvt_pk_bf16_f32 v135, v96, v97
	v_mul_f32_e32 v147, v93, v93
	v_cvt_pk_bf16_f32 v136, v90, v91
	v_cvt_pk_bf16_f32 v137, v92, v93
	global_store_dwordx4 v[142:143], v[134:137], off
	global_load_dwordx4 v[220:223], v241, s[52:53]
	global_load_dwordx4 v[224:227], v241, s[52:53] offset:16
	s_nop 0
	v_mul_f32_e32 v144, v95, v95
	v_mul_f32_e32 v145, v97, v97
	v_mul_f32_e32 v146, v91, v91
	v_fmac_f32_e32 v144, v94, v94
	v_fmac_f32_e32 v145, v96, v96
	v_fmac_f32_e32 v146, v90, v90
	v_fmac_f32_e32 v147, v92, v92
	v_add_f32_e32 v144, v144, v145
	v_add_f32_e32 v145, v146, v147
	v_add_f32_e32 v144, v144, v145
	s_waitcnt vmcnt(16)
	v_pk_add_f32 v[88:89], v[88:89], v[230:231]
	v_pk_add_f32 v[86:87], v[86:87], v[228:229]
	s_waitcnt vmcnt(15)
	v_pk_add_f32 v[84:85], v[84:85], v[234:235]
	v_pk_add_f32 v[82:83], v[82:83], v[232:233]
	v_mul_f32_e32 v134, v87, v87
	v_mul_f32_e32 v135, v89, v89
	v_mul_f32_e32 v136, v83, v83
	v_mul_f32_e32 v137, v85, v85
	v_fmac_f32_e32 v134, v86, v86
	v_fmac_f32_e32 v135, v88, v88
	v_fmac_f32_e32 v136, v82, v82
	v_fmac_f32_e32 v137, v84, v84
	v_add_f32_e32 v134, v134, v135
	v_add_f32_e32 v135, v136, v137
	v_add_f32_e32 v134, v134, v135
	v_add_f32_e32 v134, v144, v134
	ds_bpermute_b32 v135, v153, v134
	v_cvt_pk_bf16_f32 v136, v86, v87
	v_cvt_pk_bf16_f32 v137, v88, v89
	v_cvt_pk_bf16_f32 v138, v82, v83
	v_cvt_pk_bf16_f32 v139, v84, v85
	s_waitcnt lgkmcnt(0)
	v_add_f32_e32 v134, v134, v135
	ds_bpermute_b32 v135, v157, v134
	global_store_dwordx4 v[142:143], v[136:139], off offset:256
	global_load_dwordx4 v[228:231], v241, s[52:53] offset:512
	global_load_dwordx4 v[232:235], v241, s[52:53] offset:528
	s_and_saveexec_b64 s[0:1], vcc
	s_cbranch_execz .LBB0_876
	s_waitcnt lgkmcnt(0)
	v_add_f32_e32 v134, v134, v135
	ds_write_b32 v155, v134 offset:512
.LBB0_876:
	s_or_b64 exec, exec, s[0:1]
	v_or_b32_e32 v134, 48, v132
	s_waitcnt lgkmcnt(0)
	v_ashrrev_i32_e32 v135, 31, v134
	v_lshlrev_b64 v[134:135], 10, v[134:135]
	v_lshl_add_u64 v[142:143], v[134:135], 0, v[130:131]
	v_lshl_add_u64 v[144:145], v[142:143], 2, s[52:53]
	v_lshl_add_u64 v[142:143], v[142:143], 1, s[8:9]
	s_waitcnt vmcnt(16)
	v_pk_add_f32 v[80:81], v[80:81], v[190:191]
	v_pk_add_f32 v[78:79], v[78:79], v[188:189]
	s_waitcnt vmcnt(15)
	v_pk_add_f32 v[76:77], v[76:77], v[194:195]
	v_pk_add_f32 v[74:75], v[74:75], v[192:193]
	v_cvt_pk_bf16_f32 v134, v78, v79
	v_cvt_pk_bf16_f32 v135, v80, v81
	v_mul_f32_e32 v147, v77, v77
	v_cvt_pk_bf16_f32 v136, v74, v75
	v_cvt_pk_bf16_f32 v137, v76, v77
	global_store_dwordx4 v[142:143], v[134:137], off
	global_load_dwordx4 v[188:191], v242, s[52:53]
	global_load_dwordx4 v[192:195], v242, s[52:53] offset:16
	s_nop 0
	v_mul_f32_e32 v144, v79, v79
	v_mul_f32_e32 v145, v81, v81
	v_mul_f32_e32 v146, v75, v75
	v_fmac_f32_e32 v144, v78, v78
	v_fmac_f32_e32 v145, v80, v80
	v_fmac_f32_e32 v146, v74, v74
	v_fmac_f32_e32 v147, v76, v76
	v_add_f32_e32 v144, v144, v145
	v_add_f32_e32 v145, v146, v147
	v_add_f32_e32 v144, v144, v145
	s_waitcnt vmcnt(16)
	v_pk_add_f32 v[72:73], v[72:73], v[198:199]
	v_pk_add_f32 v[70:71], v[70:71], v[196:197]
	s_waitcnt vmcnt(15)
	v_pk_add_f32 v[68:69], v[68:69], v[202:203]
	v_pk_add_f32 v[66:67], v[66:67], v[200:201]
	v_mul_f32_e32 v134, v71, v71
	v_mul_f32_e32 v135, v73, v73
	v_mul_f32_e32 v136, v67, v67
	v_mul_f32_e32 v137, v69, v69
	v_fmac_f32_e32 v134, v70, v70
	v_fmac_f32_e32 v135, v72, v72
	v_fmac_f32_e32 v136, v66, v66
	v_fmac_f32_e32 v137, v68, v68
	v_add_f32_e32 v134, v134, v135
	v_add_f32_e32 v135, v136, v137
	v_add_f32_e32 v134, v134, v135
	v_add_f32_e32 v134, v144, v134
	ds_bpermute_b32 v135, v153, v134
	v_cvt_pk_bf16_f32 v136, v70, v71
	v_cvt_pk_bf16_f32 v137, v72, v73
	v_cvt_pk_bf16_f32 v138, v66, v67
	v_cvt_pk_bf16_f32 v139, v68, v69
	s_waitcnt lgkmcnt(0)
	v_add_f32_e32 v134, v134, v135
	ds_bpermute_b32 v135, v157, v134
	global_store_dwordx4 v[142:143], v[136:139], off offset:256
	global_load_dwordx4 v[196:199], v242, s[52:53] offset:512
	global_load_dwordx4 v[200:203], v242, s[52:53] offset:528
	s_and_saveexec_b64 s[0:1], vcc
	s_cbranch_execz .LBB0_878
	s_waitcnt lgkmcnt(0)
	v_add_f32_e32 v134, v134, v135
	ds_write_b32 v155, v134 offset:768
.LBB0_878:
	s_or_b64 exec, exec, s[0:1]
	s_waitcnt lgkmcnt(0)
	v_lshlrev_b64 v[134:135], 10, v[132:133]
	v_lshl_add_u64 v[134:135], v[134:135], 0, v[130:131]
	s_mov_b64 s[0:1], 0x20000
	v_lshl_add_u64 v[144:145], v[134:135], 0, s[0:1]
	v_lshl_add_u64 v[146:147], v[144:145], 2, s[52:53]
	v_lshl_add_u64 v[144:145], v[144:145], 1, s[8:9]
	s_waitcnt vmcnt(16)
	v_pk_add_f32 v[64:65], v[64:65], v[206:207]
	v_pk_add_f32 v[62:63], v[62:63], v[204:205]
	s_waitcnt vmcnt(15)
	v_pk_add_f32 v[60:61], v[60:61], v[210:211]
	v_pk_add_f32 v[58:59], v[58:59], v[208:209]
	v_cvt_pk_bf16_f32 v136, v62, v63
	v_cvt_pk_bf16_f32 v137, v64, v65
	v_mul_f32_e32 v159, v61, v61
	v_cvt_pk_bf16_f32 v138, v58, v59
	v_cvt_pk_bf16_f32 v139, v60, v61
	global_store_dwordx4 v[144:145], v[136:139], off
	global_load_dwordx4 v[204:207], v243, s[52:53]
	global_load_dwordx4 v[208:211], v243, s[52:53] offset:16
	s_nop 0
	v_mul_f32_e32 v146, v63, v63
	v_mul_f32_e32 v147, v65, v65
	v_mul_f32_e32 v151, v59, v59
	v_fmac_f32_e32 v146, v62, v62
	v_fmac_f32_e32 v147, v64, v64
	v_fmac_f32_e32 v151, v58, v58
	v_fmac_f32_e32 v159, v60, v60
	v_add_f32_e32 v146, v146, v147
	v_add_f32_e32 v147, v151, v159
	v_add_f32_e32 v146, v146, v147
	v_add_u32_e32 v151, 0x80, v158
	s_waitcnt vmcnt(16)
	v_pk_add_f32 v[56:57], v[56:57], v[214:215]
	v_pk_add_f32 v[54:55], v[54:55], v[212:213]
	s_waitcnt vmcnt(15)
	v_pk_add_f32 v[52:53], v[52:53], v[218:219]
	v_pk_add_f32 v[50:51], v[50:51], v[216:217]
	v_mul_f32_e32 v136, v55, v55
	v_mul_f32_e32 v137, v57, v57
	v_mul_f32_e32 v138, v51, v51
	v_mul_f32_e32 v139, v53, v53
	v_fmac_f32_e32 v136, v54, v54
	v_fmac_f32_e32 v137, v56, v56
	v_fmac_f32_e32 v138, v50, v50
	v_fmac_f32_e32 v139, v52, v52
	v_add_f32_e32 v136, v136, v137
	v_add_f32_e32 v137, v138, v139
	v_add_f32_e32 v136, v136, v137
	v_add_f32_e32 v136, v146, v136
	ds_bpermute_b32 v137, v153, v136
	v_cvt_pk_bf16_f32 v138, v54, v55
	v_cvt_pk_bf16_f32 v139, v56, v57
	v_cvt_pk_bf16_f32 v140, v50, v51
	v_cvt_pk_bf16_f32 v141, v52, v53
	s_waitcnt lgkmcnt(0)
	v_add_f32_e32 v136, v136, v137
	ds_bpermute_b32 v137, v157, v136
	global_store_dwordx4 v[144:145], v[138:141], off offset:256
	global_load_dwordx4 v[212:215], v243, s[52:53] offset:512
	global_load_dwordx4 v[216:219], v243, s[52:53] offset:528
	s_and_saveexec_b64 s[0:1], vcc
	s_cbranch_execz .LBB0_880
	v_lshl_add_u32 v138, v151, 4, s2
	s_waitcnt lgkmcnt(0)
	v_add_f32_e32 v136, v136, v137
	ds_write_b32 v138, v136
.LBB0_880:
	s_or_b64 exec, exec, s[0:1]
	s_mov_b64 s[0:1], 0x24000
	v_lshl_add_u64 v[142:143], v[134:135], 0, s[0:1]
	v_lshl_add_u64 v[144:145], v[142:143], 2, s[52:53]
	s_waitcnt lgkmcnt(0)
	v_lshl_add_u64 v[142:143], v[142:143], 1, s[8:9]
	s_waitcnt vmcnt(16)
	v_pk_add_f32 v[48:49], v[48:49], v[222:223]
	v_pk_add_f32 v[46:47], v[46:47], v[220:221]
	s_waitcnt vmcnt(15)
	v_pk_add_f32 v[44:45], v[44:45], v[226:227]
	v_pk_add_f32 v[42:43], v[42:43], v[224:225]
	v_cvt_pk_bf16_f32 v134, v46, v47
	v_cvt_pk_bf16_f32 v135, v48, v49
	v_mul_f32_e32 v147, v45, v45
	v_cvt_pk_bf16_f32 v136, v42, v43
	v_cvt_pk_bf16_f32 v137, v44, v45
	global_store_dwordx4 v[142:143], v[134:137], off
	s_nop 0
	v_mul_f32_e32 v144, v47, v47
	v_mul_f32_e32 v145, v49, v49
	v_mul_f32_e32 v146, v43, v43
	v_fmac_f32_e32 v144, v46, v46
	v_fmac_f32_e32 v145, v48, v48
	v_fmac_f32_e32 v146, v42, v42
	v_fmac_f32_e32 v147, v44, v44
	v_add_f32_e32 v144, v144, v145
	v_add_f32_e32 v145, v146, v147
	v_add_f32_e32 v144, v144, v145
	s_waitcnt vmcnt(14)
	v_pk_add_f32 v[40:41], v[40:41], v[230:231]
	v_pk_add_f32 v[38:39], v[38:39], v[228:229]
	s_waitcnt vmcnt(13)
	v_pk_add_f32 v[36:37], v[36:37], v[234:235]
	v_pk_add_f32 v[34:35], v[34:35], v[232:233]
	v_mul_f32_e32 v134, v39, v39
	v_mul_f32_e32 v135, v41, v41
	v_mul_f32_e32 v136, v35, v35
	v_mul_f32_e32 v137, v37, v37
	v_fmac_f32_e32 v134, v38, v38
	v_fmac_f32_e32 v135, v40, v40
	v_fmac_f32_e32 v136, v34, v34
	v_fmac_f32_e32 v137, v36, v36
	v_add_f32_e32 v134, v134, v135
	v_add_f32_e32 v135, v136, v137
	v_add_f32_e32 v134, v134, v135
	v_add_f32_e32 v134, v144, v134
	ds_bpermute_b32 v135, v153, v134
	v_cvt_pk_bf16_f32 v136, v38, v39
	v_cvt_pk_bf16_f32 v137, v40, v41
	v_cvt_pk_bf16_f32 v138, v34, v35
	v_cvt_pk_bf16_f32 v139, v36, v37
	s_waitcnt lgkmcnt(0)
	v_add_f32_e32 v134, v134, v135
	ds_bpermute_b32 v135, v157, v134
	global_store_dwordx4 v[142:143], v[136:139], off offset:256
	s_and_saveexec_b64 s[0:1], vcc
	s_cbranch_execz .LBB0_882
	s_waitcnt lgkmcnt(0)
	v_add_f32_e32 v134, v134, v135
	ds_write_b32 v155, v134 offset:2304
.LBB0_882:
	s_or_b64 exec, exec, s[0:1]
	v_lshlrev_b64 v[132:133], 10, v[132:133]
	v_lshl_add_u64 v[132:133], v[132:133], 0, v[130:131]
	s_mov_b64 s[0:1], 0x28000
	v_lshl_add_u64 v[142:143], v[132:133], 0, s[0:1]
	v_lshl_add_u64 v[144:145], v[142:143], 2, s[52:53]
	s_waitcnt lgkmcnt(0)
	v_lshl_add_u64 v[142:143], v[142:143], 1, s[8:9]
	s_waitcnt vmcnt(12)
	v_pk_add_f32 v[32:33], v[32:33], v[190:191]
	v_pk_add_f32 v[30:31], v[30:31], v[188:189]
	s_waitcnt vmcnt(11)
	v_pk_add_f32 v[28:29], v[28:29], v[194:195]
	v_pk_add_f32 v[26:27], v[26:27], v[192:193]
	v_cvt_pk_bf16_f32 v134, v30, v31
	v_cvt_pk_bf16_f32 v135, v32, v33
	v_mul_f32_e32 v147, v29, v29
	v_cvt_pk_bf16_f32 v136, v26, v27
	v_cvt_pk_bf16_f32 v137, v28, v29
	global_store_dwordx4 v[142:143], v[134:137], off
	s_nop 0
	v_mul_f32_e32 v144, v31, v31
	v_mul_f32_e32 v145, v33, v33
	v_mul_f32_e32 v146, v27, v27
	v_fmac_f32_e32 v144, v30, v30
	v_fmac_f32_e32 v145, v32, v32
	v_fmac_f32_e32 v146, v26, v26
	v_fmac_f32_e32 v147, v28, v28
	v_add_f32_e32 v144, v144, v145
	v_add_f32_e32 v145, v146, v147
	v_add_f32_e32 v144, v144, v145
	s_waitcnt vmcnt(10)
	v_pk_add_f32 v[24:25], v[24:25], v[198:199]
	v_pk_add_f32 v[22:23], v[22:23], v[196:197]
	s_waitcnt vmcnt(9)
	v_pk_add_f32 v[20:21], v[20:21], v[202:203]
	v_pk_add_f32 v[18:19], v[18:19], v[200:201]
	v_mul_f32_e32 v134, v23, v23
	v_mul_f32_e32 v135, v25, v25
	v_mul_f32_e32 v136, v19, v19
	v_mul_f32_e32 v137, v21, v21
	v_fmac_f32_e32 v134, v22, v22
	v_fmac_f32_e32 v135, v24, v24
	v_fmac_f32_e32 v136, v18, v18
	v_fmac_f32_e32 v137, v20, v20
	v_add_f32_e32 v134, v134, v135
	v_add_f32_e32 v135, v136, v137
	v_add_f32_e32 v134, v134, v135
	v_add_f32_e32 v134, v144, v134
	ds_bpermute_b32 v135, v153, v134
	v_cvt_pk_bf16_f32 v136, v22, v23
	v_cvt_pk_bf16_f32 v137, v24, v25
	v_cvt_pk_bf16_f32 v138, v18, v19
	v_cvt_pk_bf16_f32 v139, v20, v21
	s_waitcnt lgkmcnt(0)
	v_add_f32_e32 v134, v134, v135
	ds_bpermute_b32 v135, v157, v134
	global_store_dwordx4 v[142:143], v[136:139], off offset:256
	s_and_saveexec_b64 s[0:1], vcc
	s_cbranch_execz .LBB0_884
	s_waitcnt lgkmcnt(0)
	v_add_f32_e32 v134, v134, v135
	ds_write_b32 v155, v134 offset:2560
.LBB0_884:
	s_or_b64 exec, exec, s[0:1]
	s_mov_b64 s[0:1], 0x2c000
	v_lshl_add_u64 v[136:137], v[132:133], 0, s[0:1]
	v_lshl_add_u64 v[144:145], v[136:137], 2, s[52:53]
	s_waitcnt lgkmcnt(0)
	v_lshl_add_u64 v[186:187], v[136:137], 1, s[8:9]
	s_waitcnt vmcnt(8)
	v_pk_add_f32 v[134:135], v[16:17], v[206:207]
	v_pk_add_f32 v[138:139], v[14:15], v[204:205]
	s_waitcnt vmcnt(7)
	v_pk_add_f32 v[132:133], v[12:13], v[210:211]
	v_pk_add_f32 v[136:137], v[10:11], v[208:209]
	v_cvt_pk_bf16_f32 v10, v138, v139
	v_cvt_pk_bf16_f32 v11, v134, v135
	v_mul_f32_e32 v140, v139, v139
	v_cvt_pk_bf16_f32 v12, v136, v137
	v_cvt_pk_bf16_f32 v13, v132, v133
	global_store_dwordx4 v[186:187], v[10:13], off
	s_nop 0
	v_mul_f32_e32 v141, v135, v135
	v_mul_f32_e32 v142, v137, v137
	v_mul_f32_e32 v143, v133, v133
	v_fmac_f32_e32 v140, v138, v138
	v_fmac_f32_e32 v141, v134, v134
	v_fmac_f32_e32 v142, v136, v136
	v_fmac_f32_e32 v143, v132, v132
	v_add_f32_e32 v140, v140, v141
	v_add_f32_e32 v141, v142, v143
	v_add_f32_e32 v159, v140, v141
	s_waitcnt vmcnt(6)
	v_pk_add_f32 v[140:141], v[8:9], v[214:215]
	v_pk_add_f32 v[144:145], v[6:7], v[212:213]
	s_waitcnt vmcnt(5)
	v_pk_add_f32 v[142:143], v[4:5], v[218:219]
	v_pk_add_f32 v[146:147], v[2:3], v[216:217]
	v_mul_f32_e32 v2, v145, v145
	v_mul_f32_e32 v3, v141, v141
	v_mul_f32_e32 v4, v147, v147
	v_mul_f32_e32 v5, v143, v143
	v_fmac_f32_e32 v2, v144, v144
	v_fmac_f32_e32 v3, v140, v140
	v_fmac_f32_e32 v4, v146, v146
	v_fmac_f32_e32 v5, v142, v142
	v_add_f32_e32 v2, v2, v3
	v_add_f32_e32 v3, v4, v5
	v_add_f32_e32 v2, v2, v3
	v_add_f32_e32 v2, v159, v2
	ds_bpermute_b32 v3, v153, v2
	v_cvt_pk_bf16_f32 v4, v144, v145
	v_cvt_pk_bf16_f32 v5, v140, v141
	v_cvt_pk_bf16_f32 v6, v146, v147
	v_cvt_pk_bf16_f32 v7, v142, v143
	s_waitcnt lgkmcnt(0)
	v_add_f32_e32 v2, v2, v3
	ds_bpermute_b32 v3, v157, v2
	global_store_dwordx4 v[186:187], v[4:7], off offset:256
	s_and_saveexec_b64 s[0:1], vcc
	s_cbranch_execz .LBB0_886
	s_waitcnt lgkmcnt(0)
	v_add_f32_e32 v2, v2, v3
	ds_write_b32 v155, v2 offset:2816
